# v18 plus: SALU bookkeeping moved out of the MFMA segments' tails (mid-segment ops after the barrier; gate/up and w_in loop-counter updates into the preceding load segment)
# speedup vs baseline: 1.0115x; 1.0115x over previous
; #define PG8_STAGE(bufoff, gbase, voff) do { _Pragma("unroll") for (int _i = 0; _i < 2; ++_i) \
;         __builtin_amdgcn_global_load_lds((const unsigned*)((const char*)(gbase) + (voff)[_i]), (LAS unsigned*)(lds + (bufoff) + ldsw + _i * 8192), 16, 0, 0); } while (0)
; #define PG8_LDA(dst, b, h) do { _Pragma("unroll") for (int m = 0; m < 4; ++m) _Pragma("unroll") for (int k = 0; k < 2; ++k) dst[m][k] = *(const LAS bf16x8*)(lds + PG8_SA(b, h) + aoff + m * 2048 + k * 1024); } while (0)
; #define PG8_LDB(dst, b, h) do { _Pragma("unroll") for (int n = 0; n < 2; ++n) _Pragma("unroll") for (int k = 0; k < 2; ++k) dst[n][k] = *(const LAS bf16x8*)(lds + PG8_SB(b, h) + boff + n * 2048 + k * 1024); } while (0)
; #define PG8_MMA(ai, bj, At, Bt) do { __builtin_amdgcn_s_setprio(1); _Pragma("unroll") for (int m = 0; m < 4; ++m) _Pragma("unroll") for (int n = 0; n < 2; ++n) _Pragma("unroll") for (int k = 0; k < 2; ++k) \
;         acc[ai][bj][m][n] = __builtin_amdgcn_mfma_f32_16x16x32_bf16(Bt[n][k], At[m][k], acc[ai][bj][m][n], 0, 0, 0); __builtin_amdgcn_s_setprio(0); } while (0)
; #define PG8_WAIT_V(n) asm volatile("s_waitcnt vmcnt(" #n ")" ::: "memory")
; #define PG8_WAIT_L(n) asm volatile("s_waitcnt lgkmcnt(" #n ")" ::: "memory")
; #define PG8_BAR __builtin_amdgcn_s_barrier()
; template <class Epi, class Sched>
; __device__ __forceinline__ void gemm_phase(LAS unsigned char* lds, const Gemm g, const Sched& S, const Epi& E) {
;     ...
;             const bool last = (t == nt - 2);
;             const char* a1 = cA + (size_t)(t + 1) * kstep;
;             const char* a2 = last ? nA : cA + (size_t)(t + 2) * kstep; const char* b2 = last ? nB : cB + (size_t)(t + 2) * kstep;
;             const char* a3 = a2 + kstep; const char* b3 = b2 + kstep;
;             PG8_LDB(B0, 0, 0); PG8_SCHED; PG8_LDA(At, 0, 0); PG8_STAGE(PG8_SA(1, 1), a1 + hstep, voffA);
;             PG8_WAIT_L(8); PG8_BAR; PG8_WAIT_L(0); PG8_MMA(0, 0, At, B0); PG8_BAR; PG8_SCHED;
;             PG8_LDB(B1, 0, 1); PG8_STAGE(PG8_SB(0, 0), b2, voffB);
;             PG8_BAR; PG8_WAIT_L(0); PG8_MMA(0, 1, At, B1); PG8_BAR;
;             PG8_LDA(At, 0, 1); PG8_STAGE(PG8_SA(0, 0), a2, voffA);
;             PG8_BAR; PG8_WAIT_L(0); PG8_MMA(1, 0, At, B0); PG8_BAR; PG8_SCHED;
;             PG8_STAGE(PG8_SB(0, 1), b2 + hstep, voffB);
;             PG8_WAIT_V(6); PG8_BAR; PG8_MMA(1, 1, At, B1); PG8_BAR;
.LBB0_125:
	s_add_u32 s20, s16, 0xfff80080
	s_addc_u32 s21, s17, -1
	s_add_i32 s45, 0, 0x10000
	ds_read_b128 v[138:141], v129
	ds_read_b128 v[160:163], v129 offset:1024
	ds_read_b128 v[164:167], v129 offset:2048
	ds_read_b128 v[168:171], v129 offset:3072
	s_cmp_eq_u32 s44, 28
	s_cselect_b32 s23, s7, s21
	s_cselect_b32 s22, s40, s20
	s_cselect_b32 s21, s5, s43
	s_cselect_b32 s20, s41, s42
	s_add_i32 m0, s30, 0xc000
	ds_read_b128 v[172:175], v145
	ds_read_b128 v[200:203], v145 offset:1024
	ds_read_b128 v[204:207], v145 offset:2048
	ds_read_b128 v[208:211], v145 offset:3072
	ds_read_b128 v[212:215], v145 offset:4096
	ds_read_b128 v[216:219], v145 offset:5120
	ds_read_b128 v[220:223], v145 offset:6144
	ds_read_b128 v[224:227], v145 offset:7168
	global_load_lds_dwordx4 v134, s[16:17]
	s_add_i32 m0, s30, 0xe000
	s_nop 0
	global_load_lds_dwordx4 v136, s[16:17]
	s_waitcnt lgkmcnt(8)
	s_barrier
	s_waitcnt lgkmcnt(0)
	v_mfma_f32_16x16x32_bf16 v[124:127], v[138:141], v[172:175], v[124:127]
	v_mfma_f32_16x16x32_bf16 v[120:123], v[164:167], v[172:175], v[120:123]
	v_mfma_f32_16x16x32_bf16 v[116:119], v[138:141], v[204:207], v[116:119]
	v_mfma_f32_16x16x32_bf16 v[108:111], v[164:167], v[204:207], v[108:111]
	v_mfma_f32_16x16x32_bf16 v[100:103], v[138:141], v[212:215], v[100:103]
	v_mfma_f32_16x16x32_bf16 v[92:95], v[164:167], v[212:215], v[92:95]
	v_mfma_f32_16x16x32_bf16 v[84:87], v[138:141], v[220:223], v[84:87]
	v_mfma_f32_16x16x32_bf16 v[76:79], v[164:167], v[220:223], v[76:79]
	v_mfma_f32_16x16x32_bf16 v[124:127], v[160:163], v[200:203], v[124:127]
	v_mfma_f32_16x16x32_bf16 v[120:123], v[168:171], v[200:203], v[120:123]
	v_mfma_f32_16x16x32_bf16 v[116:119], v[160:163], v[208:211], v[116:119]
	v_mfma_f32_16x16x32_bf16 v[108:111], v[168:171], v[208:211], v[108:111]
	v_mfma_f32_16x16x32_bf16 v[100:103], v[160:163], v[216:219], v[100:103]
	v_mfma_f32_16x16x32_bf16 v[92:95], v[168:171], v[216:219], v[92:95]
	v_mfma_f32_16x16x32_bf16 v[84:87], v[160:163], v[224:227], v[84:87]
	v_mfma_f32_16x16x32_bf16 v[76:79], v[168:171], v[224:227], v[76:79]
	s_barrier
	s_add_i32 s48, 0, 0x14000
	s_add_i32 s45, s45, s29
	ds_read_b128 v[228:231], v129 offset:16384
	ds_read_b128 v[232:235], v129 offset:17408
	ds_read_b128 v[236:239], v129 offset:18432
	ds_read_b128 v[240:243], v129 offset:19456
	s_add_u32 s84, s20, 0x80
	s_addc_u32 s85, s21, 0
	s_mov_b32 m0, s45
	s_nop 0
	global_load_lds_dwordx4 v148, s[20:21]
	s_add_i32 m0, s45, 0x2000
	s_nop 0
	global_load_lds_dwordx4 v128, s[20:21]
	s_barrier
	s_waitcnt lgkmcnt(0)
	v_mfma_f32_16x16x32_bf16 v[112:115], v[228:231], v[172:175], v[112:115]
	v_mfma_f32_16x16x32_bf16 v[104:107], v[236:239], v[172:175], v[104:107]
	v_mfma_f32_16x16x32_bf16 v[96:99], v[228:231], v[204:207], v[96:99]
	v_mfma_f32_16x16x32_bf16 v[88:91], v[236:239], v[204:207], v[88:91]
	v_mfma_f32_16x16x32_bf16 v[80:83], v[228:231], v[212:215], v[80:83]
	v_mfma_f32_16x16x32_bf16 v[72:75], v[236:239], v[212:215], v[72:75]
	v_mfma_f32_16x16x32_bf16 v[68:71], v[228:231], v[220:223], v[68:71]
	v_mfma_f32_16x16x32_bf16 v[64:67], v[236:239], v[220:223], v[64:67]
	v_mfma_f32_16x16x32_bf16 v[112:115], v[232:235], v[200:203], v[112:115]
	v_mfma_f32_16x16x32_bf16 v[104:107], v[240:243], v[200:203], v[104:107]
	v_mfma_f32_16x16x32_bf16 v[96:99], v[232:235], v[208:211], v[96:99]
	v_mfma_f32_16x16x32_bf16 v[88:91], v[240:243], v[208:211], v[88:91]
	v_mfma_f32_16x16x32_bf16 v[80:83], v[232:235], v[216:219], v[80:83]
	v_mfma_f32_16x16x32_bf16 v[72:75], v[240:243], v[216:219], v[72:75]
	v_mfma_f32_16x16x32_bf16 v[68:71], v[232:235], v[224:227], v[68:71]
	v_mfma_f32_16x16x32_bf16 v[64:67], v[240:243], v[224:227], v[64:67]
	s_barrier
	s_mov_b32 m0, s30
	s_add_u32 s86, s22, 0x80
	s_addc_u32 s87, s23, 0
	ds_read_b128 v[172:175], v145 offset:16384
	ds_read_b128 v[200:203], v145 offset:17408
	ds_read_b128 v[204:207], v145 offset:18432
	ds_read_b128 v[208:211], v145 offset:19456
	ds_read_b128 v[212:215], v145 offset:20480
	ds_read_b128 v[216:219], v145 offset:21504
	ds_read_b128 v[220:223], v145 offset:22528
	ds_read_b128 v[224:227], v145 offset:23552
	global_load_lds_dwordx4 v132, s[22:23]
	s_mov_b32 m0, s31
	s_nop 0
	global_load_lds_dwordx4 v130, s[22:23]
	s_barrier
	s_waitcnt lgkmcnt(0)
	v_mfma_f32_16x16x32_bf16 v[60:63], v[138:141], v[172:175], v[60:63]
	v_mfma_f32_16x16x32_bf16 v[56:59], v[164:167], v[172:175], v[56:59]
	v_mfma_f32_16x16x32_bf16 v[52:55], v[138:141], v[204:207], v[52:55]
	v_mfma_f32_16x16x32_bf16 v[44:47], v[164:167], v[204:207], v[44:47]
	v_mfma_f32_16x16x32_bf16 v[36:39], v[138:141], v[212:215], v[36:39]
	v_mfma_f32_16x16x32_bf16 v[28:31], v[164:167], v[212:215], v[28:31]
	v_mfma_f32_16x16x32_bf16 v[20:23], v[138:141], v[220:223], v[20:23]
	v_mfma_f32_16x16x32_bf16 v[12:15], v[164:167], v[220:223], v[12:15]
	v_mfma_f32_16x16x32_bf16 v[60:63], v[160:163], v[200:203], v[60:63]
	v_mfma_f32_16x16x32_bf16 v[56:59], v[168:171], v[200:203], v[56:59]
	v_mfma_f32_16x16x32_bf16 v[52:55], v[160:163], v[208:211], v[52:55]
	v_mfma_f32_16x16x32_bf16 v[44:47], v[168:171], v[208:211], v[44:47]
	v_mfma_f32_16x16x32_bf16 v[36:39], v[160:163], v[216:219], v[36:39]
	v_mfma_f32_16x16x32_bf16 v[28:31], v[168:171], v[216:219], v[28:31]
	v_mfma_f32_16x16x32_bf16 v[20:23], v[160:163], v[224:227], v[20:23]
	v_mfma_f32_16x16x32_bf16 v[12:15], v[168:171], v[224:227], v[12:15]
	s_barrier
	s_add_u32 s46, s20, 0x80000
	s_addc_u32 s47, s21, 0
	s_add_i32 s45, s48, s29
	s_mov_b32 m0, s45
	s_nop 0
	global_load_lds_dwordx4 v148, s[46:47]
	s_add_i32 m0, s45, 0x2000
	s_nop 0
	global_load_lds_dwordx4 v128, s[46:47]
	s_waitcnt vmcnt(6)
	s_barrier
; #define PG8_STAGE(bufoff, gbase, voff) do { _Pragma("unroll") for (int _i = 0; _i < 2; ++_i) \
;         __builtin_amdgcn_global_load_lds((const unsigned*)((const char*)(gbase) + (voff)[_i]), (LAS unsigned*)(lds + (bufoff) + ldsw + _i * 8192), 16, 0, 0); } while (0)
; #define PG8_LDA(dst, b, h) do { _Pragma("unroll") for (int m = 0; m < 4; ++m) _Pragma("unroll") for (int k = 0; k < 2; ++k) dst[m][k] = *(const LAS bf16x8*)(lds + PG8_SA(b, h) + aoff + m * 2048 + k * 1024); } while (0)
; #define PG8_LDB(dst, b, h) do { _Pragma("unroll") for (int n = 0; n < 2; ++n) _Pragma("unroll") for (int k = 0; k < 2; ++k) dst[n][k] = *(const LAS bf16x8*)(lds + PG8_SB(b, h) + boff + n * 2048 + k * 1024); } while (0)
; #define PG8_MMA(ai, bj, At, Bt) do { __builtin_amdgcn_s_setprio(1); _Pragma("unroll") for (int m = 0; m < 4; ++m) _Pragma("unroll") for (int n = 0; n < 2; ++n) _Pragma("unroll") for (int k = 0; k < 2; ++k) \
;         acc[ai][bj][m][n] = __builtin_amdgcn_mfma_f32_16x16x32_bf16(Bt[n][k], At[m][k], acc[ai][bj][m][n], 0, 0, 0); __builtin_amdgcn_s_setprio(0); } while (0)
; #define PG8_WAIT_V(n) asm volatile("s_waitcnt vmcnt(" #n ")" ::: "memory")
; #define PG8_WAIT_L(n) asm volatile("s_waitcnt lgkmcnt(" #n ")" ::: "memory")
; #define PG8_BAR __builtin_amdgcn_s_barrier()
; #define PG8_SCHED __builtin_amdgcn_sched_barrier(0)
; template <class Epi, class Sched>
; __device__ __forceinline__ void gemm_phase(LAS unsigned char* lds, const Gemm g, const Sched& S, const Epi& E) {
;     ...
;             PG8_WAIT_V(6); PG8_BAR; PG8_MMA(1, 1, At, B1); PG8_BAR;
;             PG8_LDB(B0, 1, 0); PG8_SCHED; PG8_LDA(At, 1, 0); PG8_STAGE(PG8_SA(0, 1), a2 + hstep, voffA);
;             PG8_WAIT_L(8); PG8_BAR; PG8_WAIT_L(0); PG8_MMA(0, 0, At, B0); PG8_BAR; PG8_SCHED;
;             PG8_LDB(B1, 1, 1); PG8_STAGE(PG8_SB(1, 0), b3, voffB);
;             PG8_BAR; PG8_WAIT_L(0); PG8_MMA(0, 1, At, B1); PG8_BAR;
;             PG8_LDA(At, 1, 1); PG8_STAGE(PG8_SA(1, 0), a3, voffA);
;             PG8_BAR; PG8_WAIT_L(0); PG8_MMA(1, 0, At, B0); PG8_BAR; PG8_SCHED;
	v_mfma_f32_16x16x32_bf16 v[48:51], v[228:231], v[172:175], v[48:51]
	v_mfma_f32_16x16x32_bf16 v[40:43], v[236:239], v[172:175], v[40:43]
	v_mfma_f32_16x16x32_bf16 v[32:35], v[228:231], v[204:207], v[32:35]
	v_mfma_f32_16x16x32_bf16 v[24:27], v[236:239], v[204:207], v[24:27]
	v_mfma_f32_16x16x32_bf16 v[16:19], v[228:231], v[212:215], v[16:19]
	v_mfma_f32_16x16x32_bf16 v[8:11], v[236:239], v[212:215], v[8:11]
	v_mfma_f32_16x16x32_bf16 v[4:7], v[228:231], v[220:223], v[4:7]
	v_mfma_f32_16x16x32_bf16 v[0:3], v[236:239], v[220:223], v[0:3]
	v_mfma_f32_16x16x32_bf16 v[48:51], v[232:235], v[200:203], v[48:51]
	v_mfma_f32_16x16x32_bf16 v[40:43], v[240:243], v[200:203], v[40:43]
	v_mfma_f32_16x16x32_bf16 v[32:35], v[232:235], v[208:211], v[32:35]
	v_mfma_f32_16x16x32_bf16 v[24:27], v[240:243], v[208:211], v[24:27]
	v_mfma_f32_16x16x32_bf16 v[16:19], v[232:235], v[216:219], v[16:19]
	v_mfma_f32_16x16x32_bf16 v[8:11], v[240:243], v[216:219], v[8:11]
	v_mfma_f32_16x16x32_bf16 v[4:7], v[232:235], v[224:227], v[4:7]
	v_mfma_f32_16x16x32_bf16 v[0:3], v[240:243], v[224:227], v[0:3]
	s_barrier
	s_add_i32 s45, 0, 0x18000
	ds_read_b128 v[138:141], v129 offset:32768
	ds_read_b128 v[160:163], v129 offset:33792
	ds_read_b128 v[164:167], v129 offset:34816
	ds_read_b128 v[168:171], v129 offset:35840
	s_add_u32 s22, s22, 0x80000
	s_addc_u32 s23, s23, 0
	s_mov_b32 m0, s33
	ds_read_b128 v[172:175], v145 offset:32768
	ds_read_b128 v[200:203], v145 offset:33792
	ds_read_b128 v[204:207], v145 offset:34816
	ds_read_b128 v[208:211], v145 offset:35840
	ds_read_b128 v[212:215], v145 offset:36864
	ds_read_b128 v[216:219], v145 offset:37888
	ds_read_b128 v[220:223], v145 offset:38912
	ds_read_b128 v[224:227], v145 offset:39936
	global_load_lds_dwordx4 v132, s[22:23]
	s_mov_b32 m0, s34
	s_nop 0
	global_load_lds_dwordx4 v130, s[22:23]
	s_waitcnt lgkmcnt(8)
	s_barrier
	s_waitcnt lgkmcnt(0)
	v_mfma_f32_16x16x32_bf16 v[124:127], v[138:141], v[172:175], v[124:127]
	v_mfma_f32_16x16x32_bf16 v[120:123], v[164:167], v[172:175], v[120:123]
	v_mfma_f32_16x16x32_bf16 v[116:119], v[138:141], v[204:207], v[116:119]
	v_mfma_f32_16x16x32_bf16 v[108:111], v[164:167], v[204:207], v[108:111]
	v_mfma_f32_16x16x32_bf16 v[100:103], v[138:141], v[212:215], v[100:103]
	v_mfma_f32_16x16x32_bf16 v[92:95], v[164:167], v[212:215], v[92:95]
	v_mfma_f32_16x16x32_bf16 v[84:87], v[138:141], v[220:223], v[84:87]
	v_mfma_f32_16x16x32_bf16 v[76:79], v[164:167], v[220:223], v[76:79]
	v_mfma_f32_16x16x32_bf16 v[124:127], v[160:163], v[200:203], v[124:127]
	v_mfma_f32_16x16x32_bf16 v[120:123], v[168:171], v[200:203], v[120:123]
	v_mfma_f32_16x16x32_bf16 v[116:119], v[160:163], v[208:211], v[116:119]
	v_mfma_f32_16x16x32_bf16 v[108:111], v[168:171], v[208:211], v[108:111]
	v_mfma_f32_16x16x32_bf16 v[100:103], v[160:163], v[216:219], v[100:103]
	v_mfma_f32_16x16x32_bf16 v[92:95], v[168:171], v[216:219], v[92:95]
	v_mfma_f32_16x16x32_bf16 v[84:87], v[160:163], v[224:227], v[84:87]
	v_mfma_f32_16x16x32_bf16 v[76:79], v[168:171], v[224:227], v[76:79]
	s_barrier
	s_add_i32 s22, 0, 0x1c000
	s_add_i32 s23, s45, s29
	s_mov_b32 m0, s23
	ds_read_b128 v[228:231], v129 offset:49152
	ds_read_b128 v[232:235], v129 offset:50176
	ds_read_b128 v[236:239], v129 offset:51200
	ds_read_b128 v[240:243], v129 offset:52224
	global_load_lds_dwordx4 v148, s[84:85]
	s_add_i32 m0, s23, 0x2000
	s_nop 0
	global_load_lds_dwordx4 v128, s[84:85]
	s_barrier
	s_waitcnt lgkmcnt(0)
	v_mfma_f32_16x16x32_bf16 v[112:115], v[228:231], v[172:175], v[112:115]
	v_mfma_f32_16x16x32_bf16 v[104:107], v[236:239], v[172:175], v[104:107]
	v_mfma_f32_16x16x32_bf16 v[96:99], v[228:231], v[204:207], v[96:99]
	v_mfma_f32_16x16x32_bf16 v[88:91], v[236:239], v[204:207], v[88:91]
	v_mfma_f32_16x16x32_bf16 v[80:83], v[228:231], v[212:215], v[80:83]
	v_mfma_f32_16x16x32_bf16 v[72:75], v[236:239], v[212:215], v[72:75]
	v_mfma_f32_16x16x32_bf16 v[68:71], v[228:231], v[220:223], v[68:71]
	v_mfma_f32_16x16x32_bf16 v[64:67], v[236:239], v[220:223], v[64:67]
	v_mfma_f32_16x16x32_bf16 v[112:115], v[232:235], v[200:203], v[112:115]
	v_mfma_f32_16x16x32_bf16 v[104:107], v[240:243], v[200:203], v[104:107]
	v_mfma_f32_16x16x32_bf16 v[96:99], v[232:235], v[208:211], v[96:99]
	v_mfma_f32_16x16x32_bf16 v[88:91], v[240:243], v[208:211], v[88:91]
	v_mfma_f32_16x16x32_bf16 v[80:83], v[232:235], v[216:219], v[80:83]
	v_mfma_f32_16x16x32_bf16 v[72:75], v[240:243], v[216:219], v[72:75]
	v_mfma_f32_16x16x32_bf16 v[68:71], v[232:235], v[224:227], v[68:71]
	v_mfma_f32_16x16x32_bf16 v[64:67], v[240:243], v[224:227], v[64:67]
	s_barrier
	s_mov_b32 m0, s35
	ds_read_b128 v[172:175], v145 offset:49152
	ds_read_b128 v[200:203], v145 offset:50176
	ds_read_b128 v[204:207], v145 offset:51200
	ds_read_b128 v[208:211], v145 offset:52224
	ds_read_b128 v[212:215], v145 offset:53248
	ds_read_b128 v[216:219], v145 offset:54272
	ds_read_b128 v[220:223], v145 offset:55296
	ds_read_b128 v[224:227], v145 offset:56320
	global_load_lds_dwordx4 v132, s[86:87]
	s_mov_b32 m0, s36
	s_nop 0
	global_load_lds_dwordx4 v130, s[86:87]
	s_barrier
	s_waitcnt lgkmcnt(0)
	v_mfma_f32_16x16x32_bf16 v[60:63], v[138:141], v[172:175], v[60:63]
	v_mfma_f32_16x16x32_bf16 v[56:59], v[164:167], v[172:175], v[56:59]
	v_mfma_f32_16x16x32_bf16 v[52:55], v[138:141], v[204:207], v[52:55]
	v_mfma_f32_16x16x32_bf16 v[44:47], v[164:167], v[204:207], v[44:47]
	v_mfma_f32_16x16x32_bf16 v[36:39], v[138:141], v[212:215], v[36:39]
	v_mfma_f32_16x16x32_bf16 v[28:31], v[164:167], v[212:215], v[28:31]
	v_mfma_f32_16x16x32_bf16 v[20:23], v[138:141], v[220:223], v[20:23]
	v_mfma_f32_16x16x32_bf16 v[12:15], v[164:167], v[220:223], v[12:15]
	v_mfma_f32_16x16x32_bf16 v[60:63], v[160:163], v[200:203], v[60:63]
	v_mfma_f32_16x16x32_bf16 v[56:59], v[168:171], v[200:203], v[56:59]
	v_mfma_f32_16x16x32_bf16 v[52:55], v[160:163], v[208:211], v[52:55]
	v_mfma_f32_16x16x32_bf16 v[44:47], v[168:171], v[208:211], v[44:47]
	v_mfma_f32_16x16x32_bf16 v[36:39], v[160:163], v[216:219], v[36:39]
	v_mfma_f32_16x16x32_bf16 v[28:31], v[168:171], v[216:219], v[28:31]
	v_mfma_f32_16x16x32_bf16 v[20:23], v[160:163], v[224:227], v[20:23]
	v_mfma_f32_16x16x32_bf16 v[12:15], v[168:171], v[224:227], v[12:15]
	s_barrier
; __device__ __forceinline__ unsigned cvt_pk_bf16(float lo, float hi) { unsigned r; asm("v_cvt_pk_bf16_f32 %0, %1, %2" : "=v"(r) : "v"(lo), "v"(hi)); return r; }
; #define PG8_STAGE(bufoff, gbase, voff) do { _Pragma("unroll") for (int _i = 0; _i < 2; ++_i) \
;         __builtin_amdgcn_global_load_lds((const unsigned*)((const char*)(gbase) + (voff)[_i]), (LAS unsigned*)(lds + (bufoff) + ldsw + _i * 8192), 16, 0, 0); } while (0)
; #define PG8_MMA(ai, bj, At, Bt) do { __builtin_amdgcn_s_setprio(1); _Pragma("unroll") for (int m = 0; m < 4; ++m) _Pragma("unroll") for (int n = 0; n < 2; ++n) _Pragma("unroll") for (int k = 0; k < 2; ++k) \
;         acc[ai][bj][m][n] = __builtin_amdgcn_mfma_f32_16x16x32_bf16(Bt[n][k], At[m][k], acc[ai][bj][m][n], 0, 0, 0); __builtin_amdgcn_s_setprio(0); } while (0)
; #define PG8_WAIT_V(n) asm volatile("s_waitcnt vmcnt(" #n ")" ::: "memory")
; #define PG8_BAR __builtin_amdgcn_s_barrier()
;     __device__ __forceinline__ void operator()(const f32x4 (&acc)[2][2][4][2], const Unit& u, int wr, int wc, int fr, int fq) const {
;         const int row0 = u.pm * BM + wr * 64 + fr, col0 = u.pn * BM + wc * 32 + 8 * fq;
; #pragma unroll
;         for (int ai = 0; ai < 2; ++ai)
; #pragma unroll
;             for (int m = 0; m < 4; ++m) { bf16_t* rowp = O + (size_t)(row0 + ai * HALF + m * 16) * ldc + col0;
; #pragma unroll
;                 for (int bj = 0; bj < 2; ++bj) { const f32x4 v0 = acc[ai][bj][m][0], v1 = acc[ai][bj][m][1];
;                     u32x4 w; w.x = cvt_pk_bf16(v0[0], v0[1]); w.y = cvt_pk_bf16(v0[2], v0[3]); w.z = cvt_pk_bf16(v1[0], v1[1]); w.w = cvt_pk_bf16(v1[2], v1[3]);
;                     *(u32x4*)(rowp + bj * HALF) = w; } }
; template <class Epi, class Sched>
; __device__ __forceinline__ void gemm_phase(LAS unsigned char* lds, const Gemm g, const Sched& S, const Epi& E) {
;     ...
;             PG8_STAGE(PG8_SB(1, 1), b3 + hstep, voffB);
;             PG8_WAIT_V(6); PG8_BAR; PG8_MMA(1, 1, At, B1); PG8_BAR;
	s_add_u32 s20, s20, 0x80080
	s_addc_u32 s21, s21, 0
	s_add_i32 s22, s22, s29
	s_mov_b32 m0, s22
	s_nop 0
	global_load_lds_dwordx4 v148, s[20:21]
	s_add_i32 m0, s22, 0x2000
	s_nop 0
	global_load_lds_dwordx4 v128, s[20:21]
	s_add_i32 s44, s44, 2
	s_add_u32 s16, s16, 0x100
	s_addc_u32 s17, s17, 0
	s_add_u32 s42, s42, 0x100
	s_addc_u32 s43, s43, 0
	s_cmp_gt_u32 s44, 29
	s_waitcnt vmcnt(6)
	s_barrier
	v_mfma_f32_16x16x32_bf16 v[48:51], v[228:231], v[172:175], v[48:51]
	v_mfma_f32_16x16x32_bf16 v[40:43], v[236:239], v[172:175], v[40:43]
	v_mfma_f32_16x16x32_bf16 v[32:35], v[228:231], v[204:207], v[32:35]
	v_mfma_f32_16x16x32_bf16 v[24:27], v[236:239], v[204:207], v[24:27]
	v_mfma_f32_16x16x32_bf16 v[16:19], v[228:231], v[212:215], v[16:19]
	v_mfma_f32_16x16x32_bf16 v[8:11], v[236:239], v[212:215], v[8:11]
	v_mfma_f32_16x16x32_bf16 v[4:7], v[228:231], v[220:223], v[4:7]
	v_mfma_f32_16x16x32_bf16 v[0:3], v[236:239], v[220:223], v[0:3]
	v_mfma_f32_16x16x32_bf16 v[48:51], v[232:235], v[200:203], v[48:51]
	v_mfma_f32_16x16x32_bf16 v[40:43], v[240:243], v[200:203], v[40:43]
	v_mfma_f32_16x16x32_bf16 v[32:35], v[232:235], v[208:211], v[32:35]
	v_mfma_f32_16x16x32_bf16 v[24:27], v[240:243], v[208:211], v[24:27]
	v_mfma_f32_16x16x32_bf16 v[16:19], v[232:235], v[216:219], v[16:19]
	v_mfma_f32_16x16x32_bf16 v[8:11], v[240:243], v[216:219], v[8:11]
	v_mfma_f32_16x16x32_bf16 v[4:7], v[232:235], v[224:227], v[4:7]
	v_mfma_f32_16x16x32_bf16 v[0:3], v[240:243], v[224:227], v[0:3]
	s_barrier
	s_cbranch_scc0 .LBB0_125
	v_lshl_add_u32 v160, s39, 8, v142
	v_lshl_or_b32 v140, s38, 8, v144
	v_ashrrev_i32_e32 v141, 31, v140
	v_mov_b64_e32 v[138:139], s[2:3]
	v_cvt_pk_bf16_f32 v68, v68, v69
	v_cvt_pk_bf16_f32 v69, v70, v71
	v_cvt_pk_bf16_f32 v70, v64, v65
	v_add_u32_e32 v64, 0x80, v160
	v_mad_i64_i32 v[146:147], s[16:17], v160, s56, v[138:139]
	v_lshlrev_b64 v[140:141], 1, v[140:141]
	v_cvt_pk_bf16_f32 v112, v112, v113
	v_cvt_pk_bf16_f32 v113, v114, v115
	v_cvt_pk_bf16_f32 v114, v104, v105
	v_or_b32_e32 v104, 16, v160
	v_mad_i64_i32 v[64:65], s[16:17], v64, s56, v[138:139]
	v_cvt_pk_bf16_f32 v48, v48, v49
	v_cvt_pk_bf16_f32 v49, v50, v51
	v_cvt_pk_bf16_f32 v50, v40, v41
	v_add_u32_e32 v40, 0x90, v160
	v_lshl_add_u64 v[146:147], v[146:147], 0, v[140:141]
	v_mad_i64_i32 v[104:105], s[16:17], v104, s56, v[138:139]
	v_cvt_pk_bf16_f32 v96, v96, v97
	v_cvt_pk_bf16_f32 v97, v98, v99
	v_cvt_pk_bf16_f32 v98, v88, v89
	v_or_b32_e32 v88, 32, v160
	v_lshl_add_u64 v[64:65], v[64:65], 0, v[140:141]
	v_mad_i64_i32 v[40:41], s[16:17], v40, s56, v[138:139]
	v_cvt_pk_bf16_f32 v32, v32, v33
	v_cvt_pk_bf16_f32 v33, v34, v35
	v_cvt_pk_bf16_f32 v34, v24, v25
	v_add_u32_e32 v24, 0xa0, v160
	v_cvt_pk_bf16_f32 v115, v106, v107
	global_store_dwordx4 v[146:147], v[112:115], off offset:256
	v_mad_i64_i32 v[88:89], s[16:17], v88, s56, v[138:139]
	s_nop 0
	v_lshl_add_u64 v[112:113], v[104:105], 0, v[140:141]
	v_cvt_pk_bf16_f32 v80, v80, v81
	v_cvt_pk_bf16_f32 v81, v82, v83
	v_cvt_pk_bf16_f32 v82, v72, v73
	v_or_b32_e32 v72, 48, v160
	v_cvt_pk_bf16_f32 v51, v42, v43
	global_store_dwordx4 v[64:65], v[48:51], off offset:256
	v_mad_i64_i32 v[24:25], s[16:17], v24, s56, v[138:139]
	s_nop 0
	v_lshl_add_u64 v[48:49], v[40:41], 0, v[140:141]
	v_cvt_pk_bf16_f32 v16, v16, v17
	v_cvt_pk_bf16_f32 v17, v18, v19
	v_cvt_pk_bf16_f32 v18, v8, v9
	v_add_u32_e32 v8, 0xb0, v160
	v_cvt_pk_bf16_f32 v99, v90, v91
	global_store_dwordx4 v[112:113], v[96:99], off offset:256
	v_mad_i64_i32 v[72:73], s[16:17], v72, s56, v[138:139]
	s_nop 0
	v_lshl_add_u64 v[96:97], v[88:89], 0, v[140:141]
	v_cvt_pk_bf16_f32 v35, v26, v27
	global_store_dwordx4 v[48:49], v[32:35], off offset:256
	v_mad_i64_i32 v[8:9], s[16:17], v8, s56, v[138:139]
	s_nop 0
	v_lshl_add_u64 v[32:33], v[24:25], 0, v[140:141]
	v_cvt_pk_bf16_f32 v83, v74, v75
	global_store_dwordx4 v[96:97], v[80:83], off offset:256
	v_cvt_pk_bf16_f32 v19, v10, v11
	global_store_dwordx4 v[32:33], v[16:19], off offset:256
	s_and_b64 vcc, exec, s[0:1]
	v_lshl_add_u64 v[80:81], v[72:73], 0, v[140:141]
	v_lshl_add_u64 v[16:17], v[8:9], 0, v[140:141]
	s_mov_b32 s38, s4
	s_mov_b32 s39, s6
	s_mov_b64 s[20:21], s[14:15]
	s_mov_b64 s[16:17], s[12:13]
	v_cvt_pk_bf16_f32 v124, v124, v125
	v_cvt_pk_bf16_f32 v125, v126, v127
	v_cvt_pk_bf16_f32 v126, v120, v121
	v_cvt_pk_bf16_f32 v127, v122, v123
	global_store_dwordx4 v[146:147], v[124:127], off
	v_cvt_pk_bf16_f32 v104, v116, v117
	v_cvt_pk_bf16_f32 v105, v118, v119
	v_cvt_pk_bf16_f32 v106, v108, v109
	v_cvt_pk_bf16_f32 v107, v110, v111
	global_store_dwordx4 v[112:113], v[104:107], off
	v_cvt_pk_bf16_f32 v88, v100, v101
	v_cvt_pk_bf16_f32 v89, v102, v103
	v_cvt_pk_bf16_f32 v90, v92, v93
	v_cvt_pk_bf16_f32 v91, v94, v95
	global_store_dwordx4 v[96:97], v[88:91], off
	v_cvt_pk_bf16_f32 v72, v84, v85
	v_cvt_pk_bf16_f32 v73, v86, v87
	v_cvt_pk_bf16_f32 v74, v76, v77
	v_cvt_pk_bf16_f32 v75, v78, v79
	global_store_dwordx4 v[80:81], v[72:75], off
	v_cvt_pk_bf16_f32 v71, v66, v67
	global_store_dwordx4 v[80:81], v[68:71], off offset:256
	v_cvt_pk_bf16_f32 v60, v60, v61
	v_cvt_pk_bf16_f32 v61, v62, v63
	v_cvt_pk_bf16_f32 v62, v56, v57
	v_cvt_pk_bf16_f32 v63, v58, v59
	global_store_dwordx4 v[64:65], v[60:63], off
	v_cvt_pk_bf16_f32 v40, v52, v53
	v_cvt_pk_bf16_f32 v41, v54, v55
	v_cvt_pk_bf16_f32 v42, v44, v45
	v_cvt_pk_bf16_f32 v43, v46, v47
	global_store_dwordx4 v[48:49], v[40:43], off
	v_cvt_pk_bf16_f32 v24, v36, v37
	v_cvt_pk_bf16_f32 v25, v38, v39
	v_cvt_pk_bf16_f32 v26, v28, v29
	v_cvt_pk_bf16_f32 v27, v30, v31
	global_store_dwordx4 v[32:33], v[24:27], off
	v_cvt_pk_bf16_f32 v8, v20, v21
	v_cvt_pk_bf16_f32 v9, v22, v23
	v_cvt_pk_bf16_f32 v10, v12, v13
	v_cvt_pk_bf16_f32 v11, v14, v15
	global_store_dwordx4 v[16:17], v[8:11], off
	v_cvt_pk_bf16_f32 v4, v4, v5
	v_cvt_pk_bf16_f32 v5, v6, v7
	v_cvt_pk_bf16_f32 v6, v0, v1
	v_cvt_pk_bf16_f32 v7, v2, v3
	global_store_dwordx4 v[16:17], v[4:7], off offset:256
	s_cbranch_vccz .LBB0_118
	s_waitcnt vmcnt(0)
	s_cmpk_gt_u32 s24, 0xff
	s_cbranch_scc1 .LBB0_129
	s_barrier

; #define PG8_STAGE(bufoff, gbase, voff) do { _Pragma("unroll") for (int _i = 0; _i < 2; ++_i) \
;         __builtin_amdgcn_global_load_lds((const unsigned*)((const char*)(gbase) + (voff)[_i]), (LAS unsigned*)(lds + (bufoff) + ldsw + _i * 8192), 16, 0, 0); } while (0)
; #define PG8_LDA(dst, b, h) do { _Pragma("unroll") for (int m = 0; m < 4; ++m) _Pragma("unroll") for (int k = 0; k < 2; ++k) dst[m][k] = *(const LAS bf16x8*)(lds + PG8_SA(b, h) + aoff + m * 2048 + k * 1024); } while (0)
; #define PG8_LDB(dst, b, h) do { _Pragma("unroll") for (int n = 0; n < 2; ++n) _Pragma("unroll") for (int k = 0; k < 2; ++k) dst[n][k] = *(const LAS bf16x8*)(lds + PG8_SB(b, h) + boff + n * 2048 + k * 1024); } while (0)
; #define PG8_MMA(ai, bj, At, Bt) do { __builtin_amdgcn_s_setprio(1); _Pragma("unroll") for (int m = 0; m < 4; ++m) _Pragma("unroll") for (int n = 0; n < 2; ++n) _Pragma("unroll") for (int k = 0; k < 2; ++k) \
;         acc[ai][bj][m][n] = __builtin_amdgcn_mfma_f32_16x16x32_bf16(Bt[n][k], At[m][k], acc[ai][bj][m][n], 0, 0, 0); __builtin_amdgcn_s_setprio(0); } while (0)
; #define PG8_WAIT_V(n) asm volatile("s_waitcnt vmcnt(" #n ")" ::: "memory")
; #define PG8_WAIT_L(n) asm volatile("s_waitcnt lgkmcnt(" #n ")" ::: "memory")
; template <class Epi, class Sched>
; __device__ __forceinline__ void gemm_phase(LAS unsigned char* lds, const Gemm g, const Sched& S, const Epi& E) {
;     ...
;         for (int t = 0; t < nt; t += 2) {
;             const bool last = (t == nt - 2);
;             const char* a1 = cA + (size_t)(t + 1) * kstep;
;             const char* a2 = last ? nA : cA + (size_t)(t + 2) * kstep; const char* b2 = last ? nB : cB + (size_t)(t + 2) * kstep;
;             const char* a3 = a2 + kstep; const char* b3 = b2 + kstep;
;             PG8_LDB(B0, 0, 0); PG8_SCHED; PG8_LDA(At, 0, 0); PG8_STAGE(PG8_SA(1, 1), a1 + hstep, voffA);
;             PG8_WAIT_L(8); PG8_BAR; PG8_WAIT_L(0); PG8_MMA(0, 0, At, B0); PG8_BAR; PG8_SCHED;
;             PG8_LDB(B1, 0, 1); PG8_STAGE(PG8_SB(0, 0), b2, voffB);
;             PG8_BAR; PG8_WAIT_L(0); PG8_MMA(0, 1, At, B1); PG8_BAR;
;             PG8_LDA(At, 0, 1); PG8_STAGE(PG8_SA(0, 0), a2, voffA);
;             PG8_BAR; PG8_WAIT_L(0); PG8_MMA(1, 0, At, B0); PG8_BAR; PG8_SCHED;
;             PG8_STAGE(PG8_SB(0, 1), b2 + hstep, voffB);
;             PG8_WAIT_V(6); PG8_BAR; PG8_MMA(1, 1, At, B1); PG8_BAR;
.LBB0_170:
	s_add_i32 s53, s22, 2
	s_add_u32 s20, s16, 0x100
	s_addc_u32 s21, s17, 0
	s_add_i32 s54, 0, 0x10000
	ds_read_b128 v[128:131], v141
	ds_read_b128 v[132:135], v141 offset:1024
	ds_read_b128 v[136:139], v141 offset:2048
	ds_read_b128 v[160:163], v141 offset:3072
	s_cmp_eq_u32 s15, s22
	s_cselect_b32 s22, s4, s51
	s_cselect_b32 s25, s7, s21
	s_cselect_b32 s24, s6, s20
	s_cselect_b32 s23, s5, s52
	s_add_i32 m0, s35, 0xc000
	ds_read_b128 v[164:167], v173
	ds_read_b128 v[174:177], v173 offset:1024
	ds_read_b128 v[200:203], v173 offset:2048
	ds_read_b128 v[204:207], v173 offset:3072
	ds_read_b128 v[208:211], v173 offset:4096
	ds_read_b128 v[212:215], v173 offset:5120
	ds_read_b128 v[216:219], v173 offset:6144
	ds_read_b128 v[220:223], v173 offset:7168
	global_load_lds_dwordx4 v142, s[16:17]
	s_add_i32 m0, s35, 0xe000
	s_nop 0
	global_load_lds_dwordx4 v144, s[16:17]
	s_waitcnt lgkmcnt(8)
	s_barrier
	s_waitcnt lgkmcnt(0)
	v_mfma_f32_16x16x32_bf16 v[124:127], v[128:131], v[164:167], v[124:127]
	v_mfma_f32_16x16x32_bf16 v[120:123], v[136:139], v[164:167], v[120:123]
	v_mfma_f32_16x16x32_bf16 v[116:119], v[128:131], v[200:203], v[116:119]
	v_mfma_f32_16x16x32_bf16 v[112:115], v[136:139], v[200:203], v[112:115]
	v_mfma_f32_16x16x32_bf16 v[100:103], v[128:131], v[208:211], v[100:103]
	v_mfma_f32_16x16x32_bf16 v[96:99], v[136:139], v[208:211], v[96:99]
	v_mfma_f32_16x16x32_bf16 v[84:87], v[128:131], v[216:219], v[84:87]
	v_mfma_f32_16x16x32_bf16 v[80:83], v[136:139], v[216:219], v[80:83]
	v_mfma_f32_16x16x32_bf16 v[124:127], v[132:135], v[174:177], v[124:127]
	v_mfma_f32_16x16x32_bf16 v[120:123], v[160:163], v[174:177], v[120:123]
	v_mfma_f32_16x16x32_bf16 v[116:119], v[132:135], v[204:207], v[116:119]
	v_mfma_f32_16x16x32_bf16 v[112:115], v[160:163], v[204:207], v[112:115]
	v_mfma_f32_16x16x32_bf16 v[100:103], v[132:135], v[212:215], v[100:103]
	v_mfma_f32_16x16x32_bf16 v[96:99], v[160:163], v[212:215], v[96:99]
	v_mfma_f32_16x16x32_bf16 v[84:87], v[132:135], v[220:223], v[84:87]
	v_mfma_f32_16x16x32_bf16 v[80:83], v[160:163], v[220:223], v[80:83]
	s_barrier
	s_add_i32 s55, 0, 0x14000
	s_add_i32 s16, s54, s29
	ds_read_b128 v[224:227], v141 offset:16384
	ds_read_b128 v[228:231], v141 offset:17408
	ds_read_b128 v[232:235], v141 offset:18432
	ds_read_b128 v[236:239], v141 offset:19456
	s_add_u32 s84, s22, 0x80
	s_addc_u32 s85, s23, 0
	s_mov_b32 m0, s16
	s_nop 0
	global_load_lds_dwordx4 v148, s[22:23]
	s_add_i32 m0, s16, 0x2000
	s_nop 0
	global_load_lds_dwordx4 v140, s[22:23]
	s_barrier
	s_waitcnt lgkmcnt(0)
	v_mfma_f32_16x16x32_bf16 v[108:111], v[224:227], v[164:167], v[108:111]
	v_mfma_f32_16x16x32_bf16 v[104:107], v[232:235], v[164:167], v[104:107]
	v_mfma_f32_16x16x32_bf16 v[92:95], v[224:227], v[200:203], v[92:95]
	v_mfma_f32_16x16x32_bf16 v[88:91], v[232:235], v[200:203], v[88:91]
	v_mfma_f32_16x16x32_bf16 v[76:79], v[224:227], v[208:211], v[76:79]
	v_mfma_f32_16x16x32_bf16 v[72:75], v[232:235], v[208:211], v[72:75]
	v_mfma_f32_16x16x32_bf16 v[68:71], v[224:227], v[216:219], v[68:71]
	v_mfma_f32_16x16x32_bf16 v[64:67], v[232:235], v[216:219], v[64:67]
	v_mfma_f32_16x16x32_bf16 v[108:111], v[228:231], v[174:177], v[108:111]
	v_mfma_f32_16x16x32_bf16 v[104:107], v[236:239], v[174:177], v[104:107]
	v_mfma_f32_16x16x32_bf16 v[92:95], v[228:231], v[204:207], v[92:95]
	v_mfma_f32_16x16x32_bf16 v[88:91], v[236:239], v[204:207], v[88:91]
	v_mfma_f32_16x16x32_bf16 v[76:79], v[228:231], v[212:215], v[76:79]
	v_mfma_f32_16x16x32_bf16 v[72:75], v[236:239], v[212:215], v[72:75]
	v_mfma_f32_16x16x32_bf16 v[68:71], v[228:231], v[220:223], v[68:71]
	v_mfma_f32_16x16x32_bf16 v[64:67], v[236:239], v[220:223], v[64:67]
	s_barrier
	s_mov_b32 m0, s35
	s_add_u32 s86, s24, 0x80
	s_addc_u32 s87, s25, 0
	ds_read_b128 v[164:167], v173 offset:16384
	ds_read_b128 v[174:177], v173 offset:17408
	ds_read_b128 v[200:203], v173 offset:18432
	ds_read_b128 v[204:207], v173 offset:19456
	ds_read_b128 v[208:211], v173 offset:20480
	ds_read_b128 v[212:215], v173 offset:21504
	ds_read_b128 v[216:219], v173 offset:22528
	ds_read_b128 v[220:223], v173 offset:23552
	global_load_lds_dwordx4 v148, s[24:25]
	s_mov_b32 m0, s36
	s_nop 0
	global_load_lds_dwordx4 v140, s[24:25]
	s_barrier
	s_waitcnt lgkmcnt(0)
	v_mfma_f32_16x16x32_bf16 v[60:63], v[128:131], v[164:167], v[60:63]
	v_mfma_f32_16x16x32_bf16 v[56:59], v[136:139], v[164:167], v[56:59]
	v_mfma_f32_16x16x32_bf16 v[52:55], v[128:131], v[200:203], v[52:55]
	v_mfma_f32_16x16x32_bf16 v[48:51], v[136:139], v[200:203], v[48:51]
	v_mfma_f32_16x16x32_bf16 v[36:39], v[128:131], v[208:211], v[36:39]
	v_mfma_f32_16x16x32_bf16 v[32:35], v[136:139], v[208:211], v[32:35]
	v_mfma_f32_16x16x32_bf16 v[20:23], v[128:131], v[216:219], v[20:23]
	v_mfma_f32_16x16x32_bf16 v[16:19], v[136:139], v[216:219], v[16:19]
	v_mfma_f32_16x16x32_bf16 v[60:63], v[132:135], v[174:177], v[60:63]
	v_mfma_f32_16x16x32_bf16 v[56:59], v[160:163], v[174:177], v[56:59]
	v_mfma_f32_16x16x32_bf16 v[52:55], v[132:135], v[204:207], v[52:55]
	v_mfma_f32_16x16x32_bf16 v[48:51], v[160:163], v[204:207], v[48:51]
	v_mfma_f32_16x16x32_bf16 v[36:39], v[132:135], v[212:215], v[36:39]
	v_mfma_f32_16x16x32_bf16 v[32:35], v[160:163], v[212:215], v[32:35]
	v_mfma_f32_16x16x32_bf16 v[20:23], v[132:135], v[220:223], v[20:23]
	v_mfma_f32_16x16x32_bf16 v[16:19], v[160:163], v[220:223], v[16:19]
	s_barrier
	s_add_u32 s16, s22, 0x160000
	s_addc_u32 s17, s23, 0
	s_add_i32 s54, s55, s29
	s_mov_b32 m0, s54
	s_nop 0
	global_load_lds_dwordx4 v148, s[16:17]
	s_add_i32 m0, s54, 0x2000
	s_nop 0
	global_load_lds_dwordx4 v140, s[16:17]
	s_waitcnt vmcnt(6)
	s_barrier
; #define PG8_STAGE(bufoff, gbase, voff) do { _Pragma("unroll") for (int _i = 0; _i < 2; ++_i) \
;         __builtin_amdgcn_global_load_lds((const unsigned*)((const char*)(gbase) + (voff)[_i]), (LAS unsigned*)(lds + (bufoff) + ldsw + _i * 8192), 16, 0, 0); } while (0)
; #define PG8_LDA(dst, b, h) do { _Pragma("unroll") for (int m = 0; m < 4; ++m) _Pragma("unroll") for (int k = 0; k < 2; ++k) dst[m][k] = *(const LAS bf16x8*)(lds + PG8_SA(b, h) + aoff + m * 2048 + k * 1024); } while (0)
; #define PG8_LDB(dst, b, h) do { _Pragma("unroll") for (int n = 0; n < 2; ++n) _Pragma("unroll") for (int k = 0; k < 2; ++k) dst[n][k] = *(const LAS bf16x8*)(lds + PG8_SB(b, h) + boff + n * 2048 + k * 1024); } while (0)
; #define PG8_MMA(ai, bj, At, Bt) do { __builtin_amdgcn_s_setprio(1); _Pragma("unroll") for (int m = 0; m < 4; ++m) _Pragma("unroll") for (int n = 0; n < 2; ++n) _Pragma("unroll") for (int k = 0; k < 2; ++k) \
;         acc[ai][bj][m][n] = __builtin_amdgcn_mfma_f32_16x16x32_bf16(Bt[n][k], At[m][k], acc[ai][bj][m][n], 0, 0, 0); __builtin_amdgcn_s_setprio(0); } while (0)
; #define PG8_WAIT_V(n) asm volatile("s_waitcnt vmcnt(" #n ")" ::: "memory")
; #define PG8_WAIT_L(n) asm volatile("s_waitcnt lgkmcnt(" #n ")" ::: "memory")
; #define PG8_BAR __builtin_amdgcn_s_barrier()
; #define PG8_SCHED __builtin_amdgcn_sched_barrier(0)
; template <class Epi, class Sched>
; __device__ __forceinline__ void gemm_phase(LAS unsigned char* lds, const Gemm g, const Sched& S, const Epi& E) {
;     ...
;             PG8_WAIT_V(6); PG8_BAR; PG8_MMA(1, 1, At, B1); PG8_BAR;
;             PG8_LDB(B0, 1, 0); PG8_SCHED; PG8_LDA(At, 1, 0); PG8_STAGE(PG8_SA(0, 1), a2 + hstep, voffA);
;             PG8_WAIT_L(8); PG8_BAR; PG8_WAIT_L(0); PG8_MMA(0, 0, At, B0); PG8_BAR; PG8_SCHED;
;             PG8_LDB(B1, 1, 1); PG8_STAGE(PG8_SB(1, 0), b3, voffB);
;             PG8_BAR; PG8_WAIT_L(0); PG8_MMA(0, 1, At, B1); PG8_BAR;
;             PG8_LDA(At, 1, 1); PG8_STAGE(PG8_SA(1, 0), a3, voffA);
;             PG8_BAR; PG8_WAIT_L(0); PG8_MMA(1, 0, At, B0); PG8_BAR; PG8_SCHED;
	v_mfma_f32_16x16x32_bf16 v[44:47], v[224:227], v[164:167], v[44:47]
	v_mfma_f32_16x16x32_bf16 v[40:43], v[232:235], v[164:167], v[40:43]
	v_mfma_f32_16x16x32_bf16 v[28:31], v[224:227], v[200:203], v[28:31]
	v_mfma_f32_16x16x32_bf16 v[24:27], v[232:235], v[200:203], v[24:27]
	v_mfma_f32_16x16x32_bf16 v[12:15], v[224:227], v[208:211], v[12:15]
	v_mfma_f32_16x16x32_bf16 v[8:11], v[232:235], v[208:211], v[8:11]
	v_mfma_f32_16x16x32_bf16 v[4:7], v[224:227], v[216:219], v[4:7]
	v_mfma_f32_16x16x32_bf16 v[0:3], v[232:235], v[216:219], v[0:3]
	v_mfma_f32_16x16x32_bf16 v[44:47], v[228:231], v[174:177], v[44:47]
	v_mfma_f32_16x16x32_bf16 v[40:43], v[236:239], v[174:177], v[40:43]
	v_mfma_f32_16x16x32_bf16 v[28:31], v[228:231], v[204:207], v[28:31]
	v_mfma_f32_16x16x32_bf16 v[24:27], v[236:239], v[204:207], v[24:27]
	v_mfma_f32_16x16x32_bf16 v[12:15], v[228:231], v[212:215], v[12:15]
	v_mfma_f32_16x16x32_bf16 v[8:11], v[236:239], v[212:215], v[8:11]
	v_mfma_f32_16x16x32_bf16 v[4:7], v[228:231], v[220:223], v[4:7]
	v_mfma_f32_16x16x32_bf16 v[0:3], v[236:239], v[220:223], v[0:3]
	s_barrier
	s_add_i32 s54, 0, 0x18000
	ds_read_b128 v[128:131], v141 offset:32768
	ds_read_b128 v[132:135], v141 offset:33792
	ds_read_b128 v[136:139], v141 offset:34816
	ds_read_b128 v[160:163], v141 offset:35840
	s_add_u32 s16, s24, 0x160000
	s_addc_u32 s17, s25, 0
	s_mov_b32 m0, s37
	ds_read_b128 v[164:167], v173 offset:32768
	ds_read_b128 v[174:177], v173 offset:33792
	ds_read_b128 v[200:203], v173 offset:34816
	ds_read_b128 v[204:207], v173 offset:35840
	ds_read_b128 v[208:211], v173 offset:36864
	ds_read_b128 v[212:215], v173 offset:37888
	ds_read_b128 v[216:219], v173 offset:38912
	ds_read_b128 v[220:223], v173 offset:39936
	global_load_lds_dwordx4 v148, s[16:17]
	s_mov_b32 m0, s38
	s_nop 0
	global_load_lds_dwordx4 v140, s[16:17]
	s_waitcnt lgkmcnt(8)
	s_barrier
	s_waitcnt lgkmcnt(0)
	v_mfma_f32_16x16x32_bf16 v[124:127], v[128:131], v[164:167], v[124:127]
	v_mfma_f32_16x16x32_bf16 v[120:123], v[136:139], v[164:167], v[120:123]
	v_mfma_f32_16x16x32_bf16 v[116:119], v[128:131], v[200:203], v[116:119]
	v_mfma_f32_16x16x32_bf16 v[112:115], v[136:139], v[200:203], v[112:115]
	v_mfma_f32_16x16x32_bf16 v[100:103], v[128:131], v[208:211], v[100:103]
	v_mfma_f32_16x16x32_bf16 v[96:99], v[136:139], v[208:211], v[96:99]
	v_mfma_f32_16x16x32_bf16 v[84:87], v[128:131], v[216:219], v[84:87]
	v_mfma_f32_16x16x32_bf16 v[80:83], v[136:139], v[216:219], v[80:83]
	v_mfma_f32_16x16x32_bf16 v[124:127], v[132:135], v[174:177], v[124:127]
	v_mfma_f32_16x16x32_bf16 v[120:123], v[160:163], v[174:177], v[120:123]
	v_mfma_f32_16x16x32_bf16 v[116:119], v[132:135], v[204:207], v[116:119]
	v_mfma_f32_16x16x32_bf16 v[112:115], v[160:163], v[204:207], v[112:115]
	v_mfma_f32_16x16x32_bf16 v[100:103], v[132:135], v[212:215], v[100:103]
	v_mfma_f32_16x16x32_bf16 v[96:99], v[160:163], v[212:215], v[96:99]
	v_mfma_f32_16x16x32_bf16 v[84:87], v[132:135], v[220:223], v[84:87]
	v_mfma_f32_16x16x32_bf16 v[80:83], v[160:163], v[220:223], v[80:83]
	s_barrier
	s_add_i32 s24, 0, 0x1c000
	s_add_i32 s16, s54, s29
	s_mov_b32 m0, s16
	ds_read_b128 v[224:227], v141 offset:49152
	ds_read_b128 v[228:231], v141 offset:50176
	ds_read_b128 v[232:235], v141 offset:51200
	ds_read_b128 v[236:239], v141 offset:52224
	global_load_lds_dwordx4 v148, s[84:85]
	s_add_i32 m0, s16, 0x2000
	s_nop 0
	global_load_lds_dwordx4 v140, s[84:85]
	s_barrier
	s_waitcnt lgkmcnt(0)
	v_mfma_f32_16x16x32_bf16 v[108:111], v[224:227], v[164:167], v[108:111]
	v_mfma_f32_16x16x32_bf16 v[104:107], v[232:235], v[164:167], v[104:107]
	v_mfma_f32_16x16x32_bf16 v[92:95], v[224:227], v[200:203], v[92:95]
	v_mfma_f32_16x16x32_bf16 v[88:91], v[232:235], v[200:203], v[88:91]
	v_mfma_f32_16x16x32_bf16 v[76:79], v[224:227], v[208:211], v[76:79]
	v_mfma_f32_16x16x32_bf16 v[72:75], v[232:235], v[208:211], v[72:75]
	v_mfma_f32_16x16x32_bf16 v[68:71], v[224:227], v[216:219], v[68:71]
	v_mfma_f32_16x16x32_bf16 v[64:67], v[232:235], v[216:219], v[64:67]
	v_mfma_f32_16x16x32_bf16 v[108:111], v[228:231], v[174:177], v[108:111]
	v_mfma_f32_16x16x32_bf16 v[104:107], v[236:239], v[174:177], v[104:107]
	v_mfma_f32_16x16x32_bf16 v[92:95], v[228:231], v[204:207], v[92:95]
	v_mfma_f32_16x16x32_bf16 v[88:91], v[236:239], v[204:207], v[88:91]
	v_mfma_f32_16x16x32_bf16 v[76:79], v[228:231], v[212:215], v[76:79]
	v_mfma_f32_16x16x32_bf16 v[72:75], v[236:239], v[212:215], v[72:75]
	v_mfma_f32_16x16x32_bf16 v[68:71], v[228:231], v[220:223], v[68:71]
	v_mfma_f32_16x16x32_bf16 v[64:67], v[236:239], v[220:223], v[64:67]
	s_barrier
	s_mov_b32 m0, s41
	ds_read_b128 v[164:167], v173 offset:49152
	ds_read_b128 v[174:177], v173 offset:50176
	ds_read_b128 v[200:203], v173 offset:51200
	ds_read_b128 v[204:207], v173 offset:52224
	ds_read_b128 v[208:211], v173 offset:53248
	ds_read_b128 v[212:215], v173 offset:54272
	ds_read_b128 v[216:219], v173 offset:55296
	ds_read_b128 v[220:223], v173 offset:56320
	global_load_lds_dwordx4 v148, s[86:87]
	s_mov_b32 m0, s42
	s_nop 0
	global_load_lds_dwordx4 v140, s[86:87]
	s_barrier
	s_waitcnt lgkmcnt(0)
	v_mfma_f32_16x16x32_bf16 v[60:63], v[128:131], v[164:167], v[60:63]
	v_mfma_f32_16x16x32_bf16 v[56:59], v[136:139], v[164:167], v[56:59]
	v_mfma_f32_16x16x32_bf16 v[52:55], v[128:131], v[200:203], v[52:55]
	v_mfma_f32_16x16x32_bf16 v[48:51], v[136:139], v[200:203], v[48:51]
	v_mfma_f32_16x16x32_bf16 v[36:39], v[128:131], v[208:211], v[36:39]
	v_mfma_f32_16x16x32_bf16 v[32:35], v[136:139], v[208:211], v[32:35]
	v_mfma_f32_16x16x32_bf16 v[20:23], v[128:131], v[216:219], v[20:23]
	v_mfma_f32_16x16x32_bf16 v[16:19], v[136:139], v[216:219], v[16:19]
	v_mfma_f32_16x16x32_bf16 v[60:63], v[132:135], v[174:177], v[60:63]
	v_mfma_f32_16x16x32_bf16 v[56:59], v[160:163], v[174:177], v[56:59]
	v_mfma_f32_16x16x32_bf16 v[52:55], v[132:135], v[204:207], v[52:55]
	v_mfma_f32_16x16x32_bf16 v[48:51], v[160:163], v[204:207], v[48:51]
	v_mfma_f32_16x16x32_bf16 v[36:39], v[132:135], v[212:215], v[36:39]
	v_mfma_f32_16x16x32_bf16 v[32:35], v[160:163], v[212:215], v[32:35]
	v_mfma_f32_16x16x32_bf16 v[20:23], v[132:135], v[220:223], v[20:23]
	v_mfma_f32_16x16x32_bf16 v[16:19], v[160:163], v[220:223], v[16:19]
	s_barrier
; #define PG8_STAGE(bufoff, gbase, voff) do { _Pragma("unroll") for (int _i = 0; _i < 2; ++_i) \
;         __builtin_amdgcn_global_load_lds((const unsigned*)((const char*)(gbase) + (voff)[_i]), (LAS unsigned*)(lds + (bufoff) + ldsw + _i * 8192), 16, 0, 0); } while (0)
; #define PG8_WAIT_V(n) asm volatile("s_waitcnt vmcnt(" #n ")" ::: "memory")
; #define PG8_BAR __builtin_amdgcn_s_barrier()
;     __device__ __forceinline__ void operator()(const f32x4 (&acc)[2][2][4][2], const Unit& u, int wr, int wc, int fr, int fq) const {
;         const int row0 = u.pm * BM + wr * 64 + fr, col0 = u.pn * BM + wc * 32 + 4 * fq;
;         if (u.slice >= 0) {
;             float* pb = P + (size_t)u.slice * 512 * DM;
; #pragma unroll
;             for (int ai = 0; ai < 2; ++ai)
; #pragma unroll
;                 for (int m = 0; m < 4; ++m) { const size_t off = (size_t)(row0 - MP + ai * HALF + m * 16) * DM + col0;
; #pragma unroll
;                     for (int bj = 0; bj < 2; ++bj)
; #pragma unroll
;                         for (int n = 0; n < 2; ++n) *(f32x4*)(pb + off + bj * HALF + n * 16) = acc[ai][bj][m][n]; }
;             return;
;         }
;         const float* base = (u.pm < 32) ? base_lo : base_hi;
; #pragma unroll
;         for (int ai = 0; ai < 2; ++ai) {
;             f32x4 bs[4][2][2];
; #pragma unroll
;             for (int m = 0; m < 4; ++m) { const size_t off = (size_t)(row0 + ai * HALF + m * 16) * DM + col0;
; #pragma unroll
;                 for (int bj = 0; bj < 2; ++bj)
; #pragma unroll
;                     for (int n = 0; n < 2; ++n) bs[m][bj][n] = *(const f32x4*)(base + off + bj * HALF + n * 16); }
; #pragma unroll
;             for (int m = 0; m < 4; ++m) { const size_t off = (size_t)(row0 + ai * HALF + m * 16) * DM + col0;
; #pragma unroll
;                 for (int bj = 0; bj < 2; ++bj)
; #pragma unroll
;                     for (int n = 0; n < 2; ++n) *(f32x4*)(out + off + bj * HALF + n * 16) = bs[m][bj][n] + scale * acc[ai][bj][m][n]; }
; template <class Epi, class Sched>
; __device__ __forceinline__ void gemm_phase(LAS unsigned char* lds, const Gemm g, const Sched& S, const Epi& E) {
;     ...
;             PG8_STAGE(PG8_SB(1, 1), b3 + hstep, voffB);
;             PG8_WAIT_V(6); PG8_BAR; PG8_MMA(1, 1, At, B1); PG8_BAR;
	s_add_u32 s16, s22, 0x160080
	s_addc_u32 s17, s23, 0
	s_add_i32 s22, s24, s29
	s_mov_b32 m0, s22
	s_nop 0
	global_load_lds_dwordx4 v148, s[16:17]
	s_add_i32 m0, s22, 0x2000
	s_nop 0
	global_load_lds_dwordx4 v140, s[16:17]
	s_waitcnt vmcnt(6)
	s_barrier
	v_mfma_f32_16x16x32_bf16 v[44:47], v[224:227], v[164:167], v[44:47]
	v_mfma_f32_16x16x32_bf16 v[40:43], v[232:235], v[164:167], v[40:43]
	v_mfma_f32_16x16x32_bf16 v[28:31], v[224:227], v[200:203], v[28:31]
	v_mfma_f32_16x16x32_bf16 v[24:27], v[232:235], v[200:203], v[24:27]
	v_mfma_f32_16x16x32_bf16 v[12:15], v[224:227], v[208:211], v[12:15]
	v_mfma_f32_16x16x32_bf16 v[8:11], v[232:235], v[208:211], v[8:11]
	v_mfma_f32_16x16x32_bf16 v[4:7], v[224:227], v[216:219], v[4:7]
	v_mfma_f32_16x16x32_bf16 v[0:3], v[232:235], v[216:219], v[0:3]
	v_mfma_f32_16x16x32_bf16 v[44:47], v[228:231], v[174:177], v[44:47]
	v_mfma_f32_16x16x32_bf16 v[40:43], v[236:239], v[174:177], v[40:43]
	v_mfma_f32_16x16x32_bf16 v[28:31], v[228:231], v[204:207], v[28:31]
	v_mfma_f32_16x16x32_bf16 v[24:27], v[236:239], v[204:207], v[24:27]
	v_mfma_f32_16x16x32_bf16 v[12:15], v[228:231], v[212:215], v[12:15]
	v_mfma_f32_16x16x32_bf16 v[8:11], v[236:239], v[212:215], v[8:11]
	v_mfma_f32_16x16x32_bf16 v[4:7], v[228:231], v[220:223], v[4:7]
	v_mfma_f32_16x16x32_bf16 v[0:3], v[236:239], v[220:223], v[0:3]
	s_add_u32 s51, s51, 0x100
	s_addc_u32 s52, s52, 0
	s_cmp_ge_i32 s53, s50
	s_mov_b64 s[16:17], s[20:21]
	s_mov_b32 s22, s53
	s_barrier
	s_cbranch_scc0 .LBB0_170
	v_lshl_add_u32 v146, s48, 8, v170
	v_lshl_or_b32 v160, s49, 8, v172
	s_mov_b64 s[16:17], -1
	s_cmp_lt_i32 s82, 0
	v_ashrrev_i32_e32 v161, 31, v160
	v_ashrrev_i32_e32 v147, 31, v146
	s_cbranch_scc0 .LBB0_173
	s_cmp_lt_i32 s48, 32
	s_cselect_b32 s17, s13, s61
	s_cselect_b32 s16, s12, s60
	v_lshlrev_b64 v[162:163], 2, v[160:161]
	v_lshl_add_u64 v[164:165], s[16:17], 0, v[162:163]
	v_lshlrev_b64 v[166:167], 13, v[146:147]
	v_lshl_add_u64 v[128:129], v[164:165], 0, v[166:167]
	global_load_dwordx4 v[174:177], v[128:129], off
	global_load_dwordx4 v[200:203], v[128:129], off offset:64
	global_load_dwordx4 v[204:207], v[128:129], off offset:512
	global_load_dwordx4 v[208:211], v[128:129], off offset:576
	v_or_b32_e32 v128, 16, v146
	v_ashrrev_i32_e32 v129, 31, v128
	v_lshlrev_b64 v[248:249], 13, v[128:129]
	v_lshl_add_u64 v[128:129], v[164:165], 0, v[248:249]
	global_load_dwordx4 v[212:215], v[128:129], off
	global_load_dwordx4 v[216:219], v[128:129], off offset:64
	global_load_dwordx4 v[220:223], v[128:129], off offset:512
	global_load_dwordx4 v[224:227], v[128:129], off offset:576
	v_or_b32_e32 v128, 32, v146
	v_ashrrev_i32_e32 v129, 31, v128
	v_lshlrev_b64 v[188:189], 13, v[128:129]
	v_lshl_add_u64 v[128:129], v[164:165], 0, v[188:189]
	global_load_dwordx4 v[228:231], v[128:129], off
	global_load_dwordx4 v[232:235], v[128:129], off offset:64
	global_load_dwordx4 v[236:239], v[128:129], off offset:512
	global_load_dwordx4 v[240:243], v[128:129], off offset:576
	v_or_b32_e32 v128, 48, v146
	v_ashrrev_i32_e32 v129, 31, v128
	v_lshlrev_b64 v[168:169], 13, v[128:129]
	v_lshl_add_u64 v[128:129], v[164:165], 0, v[168:169]
	global_load_dwordx4 v[244:247], v[128:129], off
	global_load_dwordx4 v[136:139], v[128:129], off offset:64
	global_load_dwordx4 v[132:135], v[128:129], off offset:512
	s_nop 0
	global_load_dwordx4 v[128:131], v[128:129], off offset:576
	v_lshl_add_u64 v[190:191], s[60:61], 0, v[166:167]
	v_lshl_add_u64 v[190:191], v[190:191], 0, v[162:163]
	v_lshl_add_u64 v[188:189], s[60:61], 0, v[188:189]
	v_lshl_add_u64 v[188:189], v[188:189], 0, v[162:163]
	v_lshl_add_u64 v[168:169], s[60:61], 0, v[168:169]
	v_lshl_add_u64 v[168:169], v[168:169], 0, v[162:163]
	s_mov_b64 s[16:17], 0x100000
	s_waitcnt vmcnt(0)
	v_pk_fma_f32 v[176:177], v[126:127], 0.5, v[176:177] op_sel_hi:[1,0,1]
	v_pk_fma_f32 v[174:175], v[124:125], 0.5, v[174:175] op_sel_hi:[1,0,1]
	global_store_dwordx4 v[190:191], v[174:177], off
	v_pk_fma_f32 v[138:139], v[82:83], 0.5, v[138:139] op_sel_hi:[1,0,1]
	s_nop 0
	v_pk_fma_f32 v[176:177], v[122:123], 0.5, v[202:203] op_sel_hi:[1,0,1]
	v_pk_fma_f32 v[174:175], v[120:121], 0.5, v[200:201] op_sel_hi:[1,0,1]
	global_store_dwordx4 v[190:191], v[174:177], off offset:64
	v_pk_fma_f32 v[136:137], v[80:81], 0.5, v[136:137] op_sel_hi:[1,0,1]
	v_pk_fma_f32 v[134:135], v[70:71], 0.5, v[134:135] op_sel_hi:[1,0,1]
	v_pk_fma_f32 v[176:177], v[110:111], 0.5, v[206:207] op_sel_hi:[1,0,1]
	v_pk_fma_f32 v[174:175], v[108:109], 0.5, v[204:205] op_sel_hi:[1,0,1]
	global_store_dwordx4 v[190:191], v[174:177], off offset:512
	v_pk_fma_f32 v[132:133], v[68:69], 0.5, v[132:133] op_sel_hi:[1,0,1]
	v_pk_fma_f32 v[130:131], v[66:67], 0.5, v[130:131] op_sel_hi:[1,0,1]
	v_pk_fma_f32 v[176:177], v[106:107], 0.5, v[210:211] op_sel_hi:[1,0,1]
	v_pk_fma_f32 v[174:175], v[104:105], 0.5, v[208:209] op_sel_hi:[1,0,1]
	global_store_dwordx4 v[190:191], v[174:177], off offset:576
	v_lshl_add_u64 v[190:191], s[60:61], 0, v[248:249]
	v_lshl_add_u64 v[190:191], v[190:191], 0, v[162:163]
	v_pk_fma_f32 v[176:177], v[118:119], 0.5, v[214:215] op_sel_hi:[1,0,1]
	v_pk_fma_f32 v[174:175], v[116:117], 0.5, v[212:213] op_sel_hi:[1,0,1]
	global_store_dwordx4 v[190:191], v[174:177], off
	v_pk_fma_f32 v[128:129], v[64:65], 0.5, v[128:129] op_sel_hi:[1,0,1]
	global_store_dwordx4 v[168:169], v[136:139], off offset:64
	v_pk_fma_f32 v[176:177], v[114:115], 0.5, v[218:219] op_sel_hi:[1,0,1]
	v_pk_fma_f32 v[174:175], v[112:113], 0.5, v[216:217] op_sel_hi:[1,0,1]
	global_store_dwordx4 v[190:191], v[174:177], off offset:64
	global_store_dwordx4 v[168:169], v[132:135], off offset:512
	global_store_dwordx4 v[168:169], v[128:131], off offset:576
;     __device__ __forceinline__ void operator()(const f32x4 (&acc)[2][2][4][2], const Unit& u, int wr, int wc, int fr, int fq) const {
;     ...
;         for (int ai = 0; ai < 2; ++ai) {
;             f32x4 bs[4][2][2];
; #pragma unroll
;             for (int m = 0; m < 4; ++m) { const size_t off = (size_t)(row0 + ai * HALF + m * 16) * DM + col0;
; #pragma unroll
;                 for (int bj = 0; bj < 2; ++bj)
; #pragma unroll
;                     for (int n = 0; n < 2; ++n) bs[m][bj][n] = *(const f32x4*)(base + off + bj * HALF + n * 16); }
; #pragma unroll
;             for (int m = 0; m < 4; ++m) { const size_t off = (size_t)(row0 + ai * HALF + m * 16) * DM + col0;
; #pragma unroll
;                 for (int bj = 0; bj < 2; ++bj)
; #pragma unroll
;                     for (int n = 0; n < 2; ++n) *(f32x4*)(out + off + bj * HALF + n * 16) = bs[m][bj][n] + scale * acc[ai][bj][m][n]; }
	v_pk_fma_f32 v[176:177], v[94:95], 0.5, v[222:223] op_sel_hi:[1,0,1]
	v_pk_fma_f32 v[174:175], v[92:93], 0.5, v[220:221] op_sel_hi:[1,0,1]
	global_store_dwordx4 v[190:191], v[174:177], off offset:512
	s_nop 1
	v_pk_fma_f32 v[176:177], v[90:91], 0.5, v[226:227] op_sel_hi:[1,0,1]
	v_pk_fma_f32 v[174:175], v[88:89], 0.5, v[224:225] op_sel_hi:[1,0,1]
	global_store_dwordx4 v[190:191], v[174:177], off offset:576
	s_nop 1
	v_pk_fma_f32 v[176:177], v[102:103], 0.5, v[230:231] op_sel_hi:[1,0,1]
	v_pk_fma_f32 v[174:175], v[100:101], 0.5, v[228:229] op_sel_hi:[1,0,1]
	global_store_dwordx4 v[188:189], v[174:177], off
	s_nop 1
	v_pk_fma_f32 v[176:177], v[98:99], 0.5, v[234:235] op_sel_hi:[1,0,1]
	v_pk_fma_f32 v[174:175], v[96:97], 0.5, v[232:233] op_sel_hi:[1,0,1]
	global_store_dwordx4 v[188:189], v[174:177], off offset:64
	s_nop 1
	v_pk_fma_f32 v[176:177], v[78:79], 0.5, v[238:239] op_sel_hi:[1,0,1]
	v_pk_fma_f32 v[174:175], v[76:77], 0.5, v[236:237] op_sel_hi:[1,0,1]
	global_store_dwordx4 v[188:189], v[174:177], off offset:512
	s_nop 1
	v_pk_fma_f32 v[176:177], v[74:75], 0.5, v[242:243] op_sel_hi:[1,0,1]
	v_pk_fma_f32 v[174:175], v[72:73], 0.5, v[240:241] op_sel_hi:[1,0,1]
	global_store_dwordx4 v[188:189], v[174:177], off offset:576
	s_nop 1
	v_pk_fma_f32 v[176:177], v[86:87], 0.5, v[246:247] op_sel_hi:[1,0,1]
	v_pk_fma_f32 v[174:175], v[84:85], 0.5, v[244:245] op_sel_hi:[1,0,1]
	global_store_dwordx4 v[168:169], v[174:177], off
	v_lshl_add_u64 v[168:169], v[166:167], 0, s[16:17]
	v_lshl_add_u64 v[128:129], v[164:165], 0, v[168:169]
	global_load_dwordx4 v[174:177], v[128:129], off
	global_load_dwordx4 v[200:203], v[128:129], off offset:64
	global_load_dwordx4 v[204:207], v[128:129], off offset:512
	global_load_dwordx4 v[208:211], v[128:129], off offset:576
	s_mov_b64 s[16:17], 0x120000
	v_lshl_add_u64 v[188:189], v[166:167], 0, s[16:17]
	v_lshl_add_u64 v[128:129], v[164:165], 0, v[188:189]
	global_load_dwordx4 v[212:215], v[128:129], off
	global_load_dwordx4 v[216:219], v[128:129], off offset:64
	global_load_dwordx4 v[220:223], v[128:129], off offset:512
	global_load_dwordx4 v[224:227], v[128:129], off offset:576
	s_mov_b64 s[16:17], 0x140000
	v_lshl_add_u64 v[190:191], v[166:167], 0, s[16:17]
	v_lshl_add_u64 v[128:129], v[164:165], 0, v[190:191]
	s_mov_b64 s[16:17], 0x160000
	global_load_dwordx4 v[228:231], v[128:129], off
	global_load_dwordx4 v[232:235], v[128:129], off offset:64
	global_load_dwordx4 v[236:239], v[128:129], off offset:512
	global_load_dwordx4 v[240:243], v[128:129], off offset:576
	v_lshl_add_u64 v[166:167], v[166:167], 0, s[16:17]
	v_lshl_add_u64 v[128:129], v[164:165], 0, v[166:167]
	global_load_dwordx4 v[244:247], v[128:129], off
	global_load_dwordx4 v[136:139], v[128:129], off offset:64
	global_load_dwordx4 v[132:135], v[128:129], off offset:512
	s_nop 0
	global_load_dwordx4 v[128:131], v[128:129], off offset:576
	v_lshl_add_u64 v[164:165], s[60:61], 0, v[168:169]
	v_lshl_add_u64 v[164:165], v[164:165], 0, v[162:163]
	s_mov_b64 s[16:17], 0
	s_waitcnt vmcnt(0)
	v_pk_fma_f32 v[176:177], v[62:63], 0.5, v[176:177] op_sel_hi:[1,0,1]
	v_pk_fma_f32 v[174:175], v[60:61], 0.5, v[174:175] op_sel_hi:[1,0,1]
	global_store_dwordx4 v[164:165], v[174:177], off
	v_pk_fma_f32 v[138:139], v[18:19], 0.5, v[138:139] op_sel_hi:[1,0,1]
	s_nop 0
	v_pk_fma_f32 v[176:177], v[58:59], 0.5, v[202:203] op_sel_hi:[1,0,1]
	v_pk_fma_f32 v[174:175], v[56:57], 0.5, v[200:201] op_sel_hi:[1,0,1]
	global_store_dwordx4 v[164:165], v[174:177], off offset:64
	v_pk_fma_f32 v[136:137], v[16:17], 0.5, v[136:137] op_sel_hi:[1,0,1]
	v_pk_fma_f32 v[134:135], v[6:7], 0.5, v[134:135] op_sel_hi:[1,0,1]
	v_pk_fma_f32 v[176:177], v[46:47], 0.5, v[206:207] op_sel_hi:[1,0,1]
	v_pk_fma_f32 v[174:175], v[44:45], 0.5, v[204:205] op_sel_hi:[1,0,1]
	global_store_dwordx4 v[164:165], v[174:177], off offset:512
	v_pk_fma_f32 v[132:133], v[4:5], 0.5, v[132:133] op_sel_hi:[1,0,1]
	v_pk_fma_f32 v[130:131], v[2:3], 0.5, v[130:131] op_sel_hi:[1,0,1]
	v_pk_fma_f32 v[176:177], v[42:43], 0.5, v[210:211] op_sel_hi:[1,0,1]
	v_pk_fma_f32 v[174:175], v[40:41], 0.5, v[208:209] op_sel_hi:[1,0,1]
	global_store_dwordx4 v[164:165], v[174:177], off offset:576
	v_lshl_add_u64 v[164:165], s[60:61], 0, v[188:189]
	v_lshl_add_u64 v[164:165], v[164:165], 0, v[162:163]
	v_pk_fma_f32 v[176:177], v[54:55], 0.5, v[214:215] op_sel_hi:[1,0,1]
	v_pk_fma_f32 v[174:175], v[52:53], 0.5, v[212:213] op_sel_hi:[1,0,1]
	global_store_dwordx4 v[164:165], v[174:177], off
	v_pk_fma_f32 v[128:129], v[0:1], 0.5, v[128:129] op_sel_hi:[1,0,1]
	s_nop 0
	v_pk_fma_f32 v[176:177], v[50:51], 0.5, v[218:219] op_sel_hi:[1,0,1]
	v_pk_fma_f32 v[174:175], v[48:49], 0.5, v[216:217] op_sel_hi:[1,0,1]
	global_store_dwordx4 v[164:165], v[174:177], off offset:64
	s_nop 1
	v_pk_fma_f32 v[176:177], v[30:31], 0.5, v[222:223] op_sel_hi:[1,0,1]
	v_pk_fma_f32 v[174:175], v[28:29], 0.5, v[220:221] op_sel_hi:[1,0,1]
	global_store_dwordx4 v[164:165], v[174:177], off offset:512
	s_nop 1
	v_pk_fma_f32 v[176:177], v[26:27], 0.5, v[226:227] op_sel_hi:[1,0,1]
	v_pk_fma_f32 v[174:175], v[24:25], 0.5, v[224:225] op_sel_hi:[1,0,1]
	global_store_dwordx4 v[164:165], v[174:177], off offset:576
	v_lshl_add_u64 v[164:165], s[60:61], 0, v[190:191]
	v_lshl_add_u64 v[164:165], v[164:165], 0, v[162:163]
	v_pk_fma_f32 v[176:177], v[38:39], 0.5, v[230:231] op_sel_hi:[1,0,1]
	v_pk_fma_f32 v[174:175], v[36:37], 0.5, v[228:229] op_sel_hi:[1,0,1]
	global_store_dwordx4 v[164:165], v[174:177], off
	s_nop 1
	v_pk_fma_f32 v[176:177], v[34:35], 0.5, v[234:235] op_sel_hi:[1,0,1]
	v_pk_fma_f32 v[174:175], v[32:33], 0.5, v[232:233] op_sel_hi:[1,0,1]
	global_store_dwordx4 v[164:165], v[174:177], off offset:64
	s_nop 1
	v_pk_fma_f32 v[176:177], v[14:15], 0.5, v[238:239] op_sel_hi:[1,0,1]
	v_pk_fma_f32 v[174:175], v[12:13], 0.5, v[236:237] op_sel_hi:[1,0,1]
	global_store_dwordx4 v[164:165], v[174:177], off offset:512
	s_nop 1
	v_pk_fma_f32 v[176:177], v[10:11], 0.5, v[242:243] op_sel_hi:[1,0,1]
	v_pk_fma_f32 v[174:175], v[8:9], 0.5, v[240:241] op_sel_hi:[1,0,1]
	global_store_dwordx4 v[164:165], v[174:177], off offset:576
	v_lshl_add_u64 v[164:165], s[60:61], 0, v[166:167]
	v_lshl_add_u64 v[162:163], v[164:165], 0, v[162:163]
	v_pk_fma_f32 v[176:177], v[22:23], 0.5, v[246:247] op_sel_hi:[1,0,1]
	v_pk_fma_f32 v[174:175], v[20:21], 0.5, v[244:245] op_sel_hi:[1,0,1]
	global_store_dwordx4 v[162:163], v[174:177], off
	global_store_dwordx4 v[162:163], v[136:139], off offset:64
	global_store_dwordx4 v[162:163], v[132:135], off offset:512
	global_store_dwordx4 v[162:163], v[128:131], off offset:576

; #define PG8_STAGE(bufoff, gbase, voff) do { _Pragma("unroll") for (int _i = 0; _i < 2; ++_i) \
;         __builtin_amdgcn_global_load_lds((const unsigned*)((const char*)(gbase) + (voff)[_i]), (LAS unsigned*)(lds + (bufoff) + ldsw + _i * 8192), 16, 0, 0); } while (0)
; #define PG8_LDA(dst, b, h) do { _Pragma("unroll") for (int m = 0; m < 4; ++m) _Pragma("unroll") for (int k = 0; k < 2; ++k) dst[m][k] = *(const LAS bf16x8*)(lds + PG8_SA(b, h) + aoff + m * 2048 + k * 1024); } while (0)
; #define PG8_LDB(dst, b, h) do { _Pragma("unroll") for (int n = 0; n < 2; ++n) _Pragma("unroll") for (int k = 0; k < 2; ++k) dst[n][k] = *(const LAS bf16x8*)(lds + PG8_SB(b, h) + boff + n * 2048 + k * 1024); } while (0)
; #define PG8_MMA(ai, bj, At, Bt) do { __builtin_amdgcn_s_setprio(1); _Pragma("unroll") for (int m = 0; m < 4; ++m) _Pragma("unroll") for (int n = 0; n < 2; ++n) _Pragma("unroll") for (int k = 0; k < 2; ++k) \
;         acc[ai][bj][m][n] = __builtin_amdgcn_mfma_f32_16x16x32_bf16(Bt[n][k], At[m][k], acc[ai][bj][m][n], 0, 0, 0); __builtin_amdgcn_s_setprio(0); } while (0)
; #define PG8_WAIT_V(n) asm volatile("s_waitcnt vmcnt(" #n ")" ::: "memory")
; #define PG8_WAIT_L(n) asm volatile("s_waitcnt lgkmcnt(" #n ")" ::: "memory")
; #define PG8_BAR __builtin_amdgcn_s_barrier()
; template <class Epi, class Sched>
; __device__ __forceinline__ void gemm_phase(LAS unsigned char* lds, const Gemm g, const Sched& S, const Epi& E) {
;     ...
;             const bool last = (t == nt - 2);
;             const char* a1 = cA + (size_t)(t + 1) * kstep;
;             const char* a2 = last ? nA : cA + (size_t)(t + 2) * kstep; const char* b2 = last ? nB : cB + (size_t)(t + 2) * kstep;
;             const char* a3 = a2 + kstep; const char* b3 = b2 + kstep;
;             PG8_LDB(B0, 0, 0); PG8_SCHED; PG8_LDA(At, 0, 0); PG8_STAGE(PG8_SA(1, 1), a1 + hstep, voffA);
;             PG8_WAIT_L(8); PG8_BAR; PG8_WAIT_L(0); PG8_MMA(0, 0, At, B0); PG8_BAR; PG8_SCHED;
;             PG8_LDB(B1, 0, 1); PG8_STAGE(PG8_SB(0, 0), b2, voffB);
;             PG8_BAR; PG8_WAIT_L(0); PG8_MMA(0, 1, At, B1); PG8_BAR;
;             PG8_LDA(At, 0, 1); PG8_STAGE(PG8_SA(0, 0), a2, voffA);
;             PG8_BAR; PG8_WAIT_L(0); PG8_MMA(1, 0, At, B0); PG8_BAR; PG8_SCHED;
;             PG8_STAGE(PG8_SB(0, 1), b2 + hstep, voffB);
;             PG8_WAIT_V(6); PG8_BAR; PG8_MMA(1, 1, At, B1); PG8_BAR;
.LBB0_213:
	s_add_u32 s20, s16, 0xfff80080
	s_addc_u32 s21, s17, -1
	s_add_i32 s45, 0, 0x10000
	ds_read_b128 v[144:147], v129
	ds_read_b128 v[160:163], v129 offset:1024
	ds_read_b128 v[164:167], v129 offset:2048
	ds_read_b128 v[168:171], v129 offset:3072
	s_cmp_eq_u32 s44, 28
	s_cselect_b32 s23, s11, s21
	s_cselect_b32 s22, s40, s20
	s_cselect_b32 s21, s7, s43
	s_cselect_b32 s20, s41, s42
	s_add_i32 m0, s30, 0xc000
	ds_read_b128 v[172:175], v143
	ds_read_b128 v[200:203], v143 offset:1024
	ds_read_b128 v[204:207], v143 offset:2048
	ds_read_b128 v[208:211], v143 offset:3072
	ds_read_b128 v[212:215], v143 offset:4096
	ds_read_b128 v[216:219], v143 offset:5120
	ds_read_b128 v[220:223], v143 offset:6144
	ds_read_b128 v[224:227], v143 offset:7168
	global_load_lds_dwordx4 v134, s[16:17]
	s_add_i32 m0, s30, 0xe000
	s_nop 0
	global_load_lds_dwordx4 v136, s[16:17]
	s_waitcnt lgkmcnt(8)
	s_barrier
	s_waitcnt lgkmcnt(0)
	v_mfma_f32_16x16x32_bf16 v[124:127], v[144:147], v[172:175], v[124:127]
	v_mfma_f32_16x16x32_bf16 v[116:119], v[164:167], v[172:175], v[116:119]
	v_mfma_f32_16x16x32_bf16 v[108:111], v[144:147], v[204:207], v[108:111]
	v_mfma_f32_16x16x32_bf16 v[100:103], v[164:167], v[204:207], v[100:103]
	v_mfma_f32_16x16x32_bf16 v[92:95], v[144:147], v[212:215], v[92:95]
	v_mfma_f32_16x16x32_bf16 v[84:87], v[164:167], v[212:215], v[84:87]
	v_mfma_f32_16x16x32_bf16 v[76:79], v[144:147], v[220:223], v[76:79]
	v_mfma_f32_16x16x32_bf16 v[68:71], v[164:167], v[220:223], v[68:71]
	v_mfma_f32_16x16x32_bf16 v[124:127], v[160:163], v[200:203], v[124:127]
	v_mfma_f32_16x16x32_bf16 v[116:119], v[168:171], v[200:203], v[116:119]
	v_mfma_f32_16x16x32_bf16 v[108:111], v[160:163], v[208:211], v[108:111]
	v_mfma_f32_16x16x32_bf16 v[100:103], v[168:171], v[208:211], v[100:103]
	v_mfma_f32_16x16x32_bf16 v[92:95], v[160:163], v[216:219], v[92:95]
	v_mfma_f32_16x16x32_bf16 v[84:87], v[168:171], v[216:219], v[84:87]
	v_mfma_f32_16x16x32_bf16 v[76:79], v[160:163], v[224:227], v[76:79]
	v_mfma_f32_16x16x32_bf16 v[68:71], v[168:171], v[224:227], v[68:71]
	s_barrier
	s_add_i32 s48, 0, 0x14000
	s_add_i32 s45, s45, s29
	ds_read_b128 v[228:231], v129 offset:16384
	ds_read_b128 v[232:235], v129 offset:17408
	ds_read_b128 v[236:239], v129 offset:18432
	ds_read_b128 v[240:243], v129 offset:19456
	s_add_u32 s84, s20, 0x80
	s_addc_u32 s85, s21, 0
	s_mov_b32 m0, s45
	s_nop 0
	global_load_lds_dwordx4 v148, s[20:21]
	s_add_i32 m0, s45, 0x2000
	s_nop 0
	global_load_lds_dwordx4 v128, s[20:21]
	s_barrier
	s_waitcnt lgkmcnt(0)
	v_mfma_f32_16x16x32_bf16 v[120:123], v[228:231], v[172:175], v[120:123]
	v_mfma_f32_16x16x32_bf16 v[112:115], v[236:239], v[172:175], v[112:115]
	v_mfma_f32_16x16x32_bf16 v[104:107], v[228:231], v[204:207], v[104:107]
	v_mfma_f32_16x16x32_bf16 v[96:99], v[236:239], v[204:207], v[96:99]
	v_mfma_f32_16x16x32_bf16 v[88:91], v[228:231], v[212:215], v[88:91]
	v_mfma_f32_16x16x32_bf16 v[80:83], v[236:239], v[212:215], v[80:83]
	v_mfma_f32_16x16x32_bf16 v[72:75], v[228:231], v[220:223], v[72:75]
	v_mfma_f32_16x16x32_bf16 v[64:67], v[236:239], v[220:223], v[64:67]
	v_mfma_f32_16x16x32_bf16 v[120:123], v[232:235], v[200:203], v[120:123]
	v_mfma_f32_16x16x32_bf16 v[112:115], v[240:243], v[200:203], v[112:115]
	v_mfma_f32_16x16x32_bf16 v[104:107], v[232:235], v[208:211], v[104:107]
	v_mfma_f32_16x16x32_bf16 v[96:99], v[240:243], v[208:211], v[96:99]
	v_mfma_f32_16x16x32_bf16 v[88:91], v[232:235], v[216:219], v[88:91]
	v_mfma_f32_16x16x32_bf16 v[80:83], v[240:243], v[216:219], v[80:83]
	v_mfma_f32_16x16x32_bf16 v[72:75], v[232:235], v[224:227], v[72:75]
	v_mfma_f32_16x16x32_bf16 v[64:67], v[240:243], v[224:227], v[64:67]
	s_barrier
	s_mov_b32 m0, s30
	s_add_u32 s86, s22, 0x80
	s_addc_u32 s87, s23, 0
	ds_read_b128 v[172:175], v143 offset:16384
	ds_read_b128 v[200:203], v143 offset:17408
	ds_read_b128 v[204:207], v143 offset:18432
	ds_read_b128 v[208:211], v143 offset:19456
	ds_read_b128 v[212:215], v143 offset:20480
	ds_read_b128 v[216:219], v143 offset:21504
	ds_read_b128 v[220:223], v143 offset:22528
	ds_read_b128 v[224:227], v143 offset:23552
	global_load_lds_dwordx4 v132, s[22:23]
	s_mov_b32 m0, s31
	s_nop 0
	global_load_lds_dwordx4 v130, s[22:23]
	s_barrier
	s_waitcnt lgkmcnt(0)
	v_mfma_f32_16x16x32_bf16 v[60:63], v[144:147], v[172:175], v[60:63]
	v_mfma_f32_16x16x32_bf16 v[52:55], v[164:167], v[172:175], v[52:55]
	v_mfma_f32_16x16x32_bf16 v[44:47], v[144:147], v[204:207], v[44:47]
	v_mfma_f32_16x16x32_bf16 v[36:39], v[164:167], v[204:207], v[36:39]
	v_mfma_f32_16x16x32_bf16 v[28:31], v[144:147], v[212:215], v[28:31]
	v_mfma_f32_16x16x32_bf16 v[20:23], v[164:167], v[212:215], v[20:23]
	v_mfma_f32_16x16x32_bf16 v[12:15], v[144:147], v[220:223], v[12:15]
	v_mfma_f32_16x16x32_bf16 v[4:7], v[164:167], v[220:223], v[4:7]
	v_mfma_f32_16x16x32_bf16 v[60:63], v[160:163], v[200:203], v[60:63]
	v_mfma_f32_16x16x32_bf16 v[52:55], v[168:171], v[200:203], v[52:55]
	v_mfma_f32_16x16x32_bf16 v[44:47], v[160:163], v[208:211], v[44:47]
	v_mfma_f32_16x16x32_bf16 v[36:39], v[168:171], v[208:211], v[36:39]
	v_mfma_f32_16x16x32_bf16 v[28:31], v[160:163], v[216:219], v[28:31]
	v_mfma_f32_16x16x32_bf16 v[20:23], v[168:171], v[216:219], v[20:23]
	v_mfma_f32_16x16x32_bf16 v[12:15], v[160:163], v[224:227], v[12:15]
	v_mfma_f32_16x16x32_bf16 v[4:7], v[168:171], v[224:227], v[4:7]
	s_barrier
	s_add_u32 s46, s20, 0x80000
	s_addc_u32 s47, s21, 0
	s_add_i32 s45, s48, s29
	s_mov_b32 m0, s45
	s_nop 0
	global_load_lds_dwordx4 v148, s[46:47]
	s_add_i32 m0, s45, 0x2000
	s_nop 0
	global_load_lds_dwordx4 v128, s[46:47]
	s_waitcnt vmcnt(6)
	s_barrier
; #define PG8_STAGE(bufoff, gbase, voff) do { _Pragma("unroll") for (int _i = 0; _i < 2; ++_i) \
;         __builtin_amdgcn_global_load_lds((const unsigned*)((const char*)(gbase) + (voff)[_i]), (LAS unsigned*)(lds + (bufoff) + ldsw + _i * 8192), 16, 0, 0); } while (0)
; #define PG8_LDA(dst, b, h) do { _Pragma("unroll") for (int m = 0; m < 4; ++m) _Pragma("unroll") for (int k = 0; k < 2; ++k) dst[m][k] = *(const LAS bf16x8*)(lds + PG8_SA(b, h) + aoff + m * 2048 + k * 1024); } while (0)
; #define PG8_LDB(dst, b, h) do { _Pragma("unroll") for (int n = 0; n < 2; ++n) _Pragma("unroll") for (int k = 0; k < 2; ++k) dst[n][k] = *(const LAS bf16x8*)(lds + PG8_SB(b, h) + boff + n * 2048 + k * 1024); } while (0)
; #define PG8_MMA(ai, bj, At, Bt) do { __builtin_amdgcn_s_setprio(1); _Pragma("unroll") for (int m = 0; m < 4; ++m) _Pragma("unroll") for (int n = 0; n < 2; ++n) _Pragma("unroll") for (int k = 0; k < 2; ++k) \
;         acc[ai][bj][m][n] = __builtin_amdgcn_mfma_f32_16x16x32_bf16(Bt[n][k], At[m][k], acc[ai][bj][m][n], 0, 0, 0); __builtin_amdgcn_s_setprio(0); } while (0)
; #define PG8_WAIT_V(n) asm volatile("s_waitcnt vmcnt(" #n ")" ::: "memory")
; #define PG8_WAIT_L(n) asm volatile("s_waitcnt lgkmcnt(" #n ")" ::: "memory")
; #define PG8_BAR __builtin_amdgcn_s_barrier()
; #define PG8_SCHED __builtin_amdgcn_sched_barrier(0)
; template <class Epi, class Sched>
; __device__ __forceinline__ void gemm_phase(LAS unsigned char* lds, const Gemm g, const Sched& S, const Epi& E) {
;     ...
;             PG8_WAIT_V(6); PG8_BAR; PG8_MMA(1, 1, At, B1); PG8_BAR;
;             PG8_LDB(B0, 1, 0); PG8_SCHED; PG8_LDA(At, 1, 0); PG8_STAGE(PG8_SA(0, 1), a2 + hstep, voffA);
;             PG8_WAIT_L(8); PG8_BAR; PG8_WAIT_L(0); PG8_MMA(0, 0, At, B0); PG8_BAR; PG8_SCHED;
;             PG8_LDB(B1, 1, 1); PG8_STAGE(PG8_SB(1, 0), b3, voffB);
;             PG8_BAR; PG8_WAIT_L(0); PG8_MMA(0, 1, At, B1); PG8_BAR;
;             PG8_LDA(At, 1, 1); PG8_STAGE(PG8_SA(1, 0), a3, voffA);
;             PG8_BAR; PG8_WAIT_L(0); PG8_MMA(1, 0, At, B0); PG8_BAR; PG8_SCHED;
	v_mfma_f32_16x16x32_bf16 v[56:59], v[228:231], v[172:175], v[56:59]
	v_mfma_f32_16x16x32_bf16 v[48:51], v[236:239], v[172:175], v[48:51]
	v_mfma_f32_16x16x32_bf16 v[40:43], v[228:231], v[204:207], v[40:43]
	v_mfma_f32_16x16x32_bf16 v[32:35], v[236:239], v[204:207], v[32:35]
	v_mfma_f32_16x16x32_bf16 v[24:27], v[228:231], v[212:215], v[24:27]
	v_mfma_f32_16x16x32_bf16 v[16:19], v[236:239], v[212:215], v[16:19]
	v_mfma_f32_16x16x32_bf16 v[8:11], v[228:231], v[220:223], v[8:11]
	v_mfma_f32_16x16x32_bf16 v[0:3], v[236:239], v[220:223], v[0:3]
	v_mfma_f32_16x16x32_bf16 v[56:59], v[232:235], v[200:203], v[56:59]
	v_mfma_f32_16x16x32_bf16 v[48:51], v[240:243], v[200:203], v[48:51]
	v_mfma_f32_16x16x32_bf16 v[40:43], v[232:235], v[208:211], v[40:43]
	v_mfma_f32_16x16x32_bf16 v[32:35], v[240:243], v[208:211], v[32:35]
	v_mfma_f32_16x16x32_bf16 v[24:27], v[232:235], v[216:219], v[24:27]
	v_mfma_f32_16x16x32_bf16 v[16:19], v[240:243], v[216:219], v[16:19]
	v_mfma_f32_16x16x32_bf16 v[8:11], v[232:235], v[224:227], v[8:11]
	v_mfma_f32_16x16x32_bf16 v[0:3], v[240:243], v[224:227], v[0:3]
	s_barrier
	s_add_i32 s45, 0, 0x18000
	ds_read_b128 v[144:147], v129 offset:32768
	ds_read_b128 v[160:163], v129 offset:33792
	ds_read_b128 v[164:167], v129 offset:34816
	ds_read_b128 v[168:171], v129 offset:35840
	s_add_u32 s22, s22, 0x80000
	s_addc_u32 s23, s23, 0
	s_mov_b32 m0, s33
	ds_read_b128 v[172:175], v143 offset:32768
	ds_read_b128 v[200:203], v143 offset:33792
	ds_read_b128 v[204:207], v143 offset:34816
	ds_read_b128 v[208:211], v143 offset:35840
	ds_read_b128 v[212:215], v143 offset:36864
	ds_read_b128 v[216:219], v143 offset:37888
	ds_read_b128 v[220:223], v143 offset:38912
	ds_read_b128 v[224:227], v143 offset:39936
	global_load_lds_dwordx4 v132, s[22:23]
	s_mov_b32 m0, s34
	s_nop 0
	global_load_lds_dwordx4 v130, s[22:23]
	s_waitcnt lgkmcnt(8)
	s_barrier
	s_waitcnt lgkmcnt(0)
	v_mfma_f32_16x16x32_bf16 v[124:127], v[144:147], v[172:175], v[124:127]
	v_mfma_f32_16x16x32_bf16 v[116:119], v[164:167], v[172:175], v[116:119]
	v_mfma_f32_16x16x32_bf16 v[108:111], v[144:147], v[204:207], v[108:111]
	v_mfma_f32_16x16x32_bf16 v[100:103], v[164:167], v[204:207], v[100:103]
	v_mfma_f32_16x16x32_bf16 v[92:95], v[144:147], v[212:215], v[92:95]
	v_mfma_f32_16x16x32_bf16 v[84:87], v[164:167], v[212:215], v[84:87]
	v_mfma_f32_16x16x32_bf16 v[76:79], v[144:147], v[220:223], v[76:79]
	v_mfma_f32_16x16x32_bf16 v[68:71], v[164:167], v[220:223], v[68:71]
	v_mfma_f32_16x16x32_bf16 v[124:127], v[160:163], v[200:203], v[124:127]
	v_mfma_f32_16x16x32_bf16 v[116:119], v[168:171], v[200:203], v[116:119]
	v_mfma_f32_16x16x32_bf16 v[108:111], v[160:163], v[208:211], v[108:111]
	v_mfma_f32_16x16x32_bf16 v[100:103], v[168:171], v[208:211], v[100:103]
	v_mfma_f32_16x16x32_bf16 v[92:95], v[160:163], v[216:219], v[92:95]
	v_mfma_f32_16x16x32_bf16 v[84:87], v[168:171], v[216:219], v[84:87]
	v_mfma_f32_16x16x32_bf16 v[76:79], v[160:163], v[224:227], v[76:79]
	v_mfma_f32_16x16x32_bf16 v[68:71], v[168:171], v[224:227], v[68:71]
	s_barrier
	s_add_i32 s22, 0, 0x1c000
	s_add_i32 s23, s45, s29
	s_mov_b32 m0, s23
	ds_read_b128 v[228:231], v129 offset:49152
	ds_read_b128 v[232:235], v129 offset:50176
	ds_read_b128 v[236:239], v129 offset:51200
	ds_read_b128 v[240:243], v129 offset:52224
	global_load_lds_dwordx4 v148, s[84:85]
	s_add_i32 m0, s23, 0x2000
	s_nop 0
	global_load_lds_dwordx4 v128, s[84:85]
	s_barrier
	s_waitcnt lgkmcnt(0)
	v_mfma_f32_16x16x32_bf16 v[120:123], v[228:231], v[172:175], v[120:123]
	v_mfma_f32_16x16x32_bf16 v[112:115], v[236:239], v[172:175], v[112:115]
	v_mfma_f32_16x16x32_bf16 v[104:107], v[228:231], v[204:207], v[104:107]
	v_mfma_f32_16x16x32_bf16 v[96:99], v[236:239], v[204:207], v[96:99]
	v_mfma_f32_16x16x32_bf16 v[88:91], v[228:231], v[212:215], v[88:91]
	v_mfma_f32_16x16x32_bf16 v[80:83], v[236:239], v[212:215], v[80:83]
	v_mfma_f32_16x16x32_bf16 v[72:75], v[228:231], v[220:223], v[72:75]
	v_mfma_f32_16x16x32_bf16 v[64:67], v[236:239], v[220:223], v[64:67]
	v_mfma_f32_16x16x32_bf16 v[120:123], v[232:235], v[200:203], v[120:123]
	v_mfma_f32_16x16x32_bf16 v[112:115], v[240:243], v[200:203], v[112:115]
	v_mfma_f32_16x16x32_bf16 v[104:107], v[232:235], v[208:211], v[104:107]
	v_mfma_f32_16x16x32_bf16 v[96:99], v[240:243], v[208:211], v[96:99]
	v_mfma_f32_16x16x32_bf16 v[88:91], v[232:235], v[216:219], v[88:91]
	v_mfma_f32_16x16x32_bf16 v[80:83], v[240:243], v[216:219], v[80:83]
	v_mfma_f32_16x16x32_bf16 v[72:75], v[232:235], v[224:227], v[72:75]
	v_mfma_f32_16x16x32_bf16 v[64:67], v[240:243], v[224:227], v[64:67]
	s_barrier
	s_mov_b32 m0, s35
	ds_read_b128 v[172:175], v143 offset:49152
	ds_read_b128 v[200:203], v143 offset:50176
	ds_read_b128 v[204:207], v143 offset:51200
	ds_read_b128 v[208:211], v143 offset:52224
	ds_read_b128 v[212:215], v143 offset:53248
	ds_read_b128 v[216:219], v143 offset:54272
	ds_read_b128 v[220:223], v143 offset:55296
	ds_read_b128 v[224:227], v143 offset:56320
	global_load_lds_dwordx4 v132, s[86:87]
	s_mov_b32 m0, s36
	s_nop 0
	global_load_lds_dwordx4 v130, s[86:87]
	s_barrier
	s_waitcnt lgkmcnt(0)
	v_mfma_f32_16x16x32_bf16 v[60:63], v[144:147], v[172:175], v[60:63]
	v_mfma_f32_16x16x32_bf16 v[52:55], v[164:167], v[172:175], v[52:55]
	v_mfma_f32_16x16x32_bf16 v[44:47], v[144:147], v[204:207], v[44:47]
	v_mfma_f32_16x16x32_bf16 v[36:39], v[164:167], v[204:207], v[36:39]
	v_mfma_f32_16x16x32_bf16 v[28:31], v[144:147], v[212:215], v[28:31]
	v_mfma_f32_16x16x32_bf16 v[20:23], v[164:167], v[212:215], v[20:23]
	v_mfma_f32_16x16x32_bf16 v[12:15], v[144:147], v[220:223], v[12:15]
	v_mfma_f32_16x16x32_bf16 v[4:7], v[164:167], v[220:223], v[4:7]
	v_mfma_f32_16x16x32_bf16 v[60:63], v[160:163], v[200:203], v[60:63]
	v_mfma_f32_16x16x32_bf16 v[52:55], v[168:171], v[200:203], v[52:55]
	v_mfma_f32_16x16x32_bf16 v[44:47], v[160:163], v[208:211], v[44:47]
	v_mfma_f32_16x16x32_bf16 v[36:39], v[168:171], v[208:211], v[36:39]
	v_mfma_f32_16x16x32_bf16 v[28:31], v[160:163], v[216:219], v[28:31]
	v_mfma_f32_16x16x32_bf16 v[20:23], v[168:171], v[216:219], v[20:23]
	v_mfma_f32_16x16x32_bf16 v[12:15], v[160:163], v[224:227], v[12:15]
	v_mfma_f32_16x16x32_bf16 v[4:7], v[168:171], v[224:227], v[4:7]
	s_barrier
; __device__ __forceinline__ unsigned cvt_pk_bf16(float lo, float hi) { unsigned r; asm("v_cvt_pk_bf16_f32 %0, %1, %2" : "=v"(r) : "v"(lo), "v"(hi)); return r; }
; #define PG8_STAGE(bufoff, gbase, voff) do { _Pragma("unroll") for (int _i = 0; _i < 2; ++_i) \
;         __builtin_amdgcn_global_load_lds((const unsigned*)((const char*)(gbase) + (voff)[_i]), (LAS unsigned*)(lds + (bufoff) + ldsw + _i * 8192), 16, 0, 0); } while (0)
; #define PG8_MMA(ai, bj, At, Bt) do { __builtin_amdgcn_s_setprio(1); _Pragma("unroll") for (int m = 0; m < 4; ++m) _Pragma("unroll") for (int n = 0; n < 2; ++n) _Pragma("unroll") for (int k = 0; k < 2; ++k) \
;         acc[ai][bj][m][n] = __builtin_amdgcn_mfma_f32_16x16x32_bf16(Bt[n][k], At[m][k], acc[ai][bj][m][n], 0, 0, 0); __builtin_amdgcn_s_setprio(0); } while (0)
; #define PG8_WAIT_V(n) asm volatile("s_waitcnt vmcnt(" #n ")" ::: "memory")
; #define PG8_BAR __builtin_amdgcn_s_barrier()
;     __device__ __forceinline__ void operator()(const f32x4 (&acc)[2][2][4][2], const Unit& u, int wr, int wc, int fr, int fq) const {
;         const int row0 = u.pm * BM + wr * 64 + fr, col0 = u.pn * HALF + wc * 32 + 8 * fq;
; #pragma unroll
;         for (int ai = 0; ai < 2; ++ai)
; #pragma unroll
;             for (int m = 0; m < 4; ++m) { bf16_t* rowp = O + (size_t)(row0 + ai * HALF + m * 16) * ldc + col0;
;                 float h[8];
; #pragma unroll
;                 for (int n = 0; n < 2; ++n)
; #pragma unroll
;                     for (int j = 0; j < 4; ++j) { const float g = acc[ai][0][m][n][j], up = acc[ai][1][m][n][j];
;                         const float e = __builtin_amdgcn_exp2f(-1.4426950408889634f * g);
;                         h[n * 4 + j] = g * __builtin_amdgcn_rcpf(1.0f + e) * up; }
;                 u32x4 w; w.x = cvt_pk_bf16(h[0], h[1]); w.y = cvt_pk_bf16(h[2], h[3]); w.z = cvt_pk_bf16(h[4], h[5]); w.w = cvt_pk_bf16(h[6], h[7]);
;                 *(u32x4*)rowp = w; }
; template <class Epi, class Sched>
; __device__ __forceinline__ void gemm_phase(LAS unsigned char* lds, const Gemm g, const Sched& S, const Epi& E) {
;     ...
;         for (int t = 0; t < nt; t += 2) {
;     ...
;             PG8_STAGE(PG8_SB(1, 1), b3 + hstep, voffB);
;             PG8_WAIT_V(6); PG8_BAR; PG8_MMA(1, 1, At, B1); PG8_BAR;
	s_add_u32 s20, s20, 0x80080
	s_addc_u32 s21, s21, 0
	s_add_i32 s22, s22, s29
	s_mov_b32 m0, s22
	s_nop 0
	global_load_lds_dwordx4 v148, s[20:21]
	s_add_i32 m0, s22, 0x2000
	s_nop 0
	global_load_lds_dwordx4 v128, s[20:21]
	s_add_i32 s44, s44, 2
	s_add_u32 s16, s16, 0x100
	s_addc_u32 s17, s17, 0
	s_add_u32 s42, s42, 0x100
	s_addc_u32 s43, s43, 0
	s_cmp_gt_u32 s44, 29
	s_waitcnt vmcnt(6)
	s_barrier
	v_mfma_f32_16x16x32_bf16 v[56:59], v[228:231], v[172:175], v[56:59]
	v_mfma_f32_16x16x32_bf16 v[48:51], v[236:239], v[172:175], v[48:51]
	v_mfma_f32_16x16x32_bf16 v[40:43], v[228:231], v[204:207], v[40:43]
	v_mfma_f32_16x16x32_bf16 v[32:35], v[236:239], v[204:207], v[32:35]
	v_mfma_f32_16x16x32_bf16 v[24:27], v[228:231], v[212:215], v[24:27]
	v_mfma_f32_16x16x32_bf16 v[16:19], v[236:239], v[212:215], v[16:19]
	v_mfma_f32_16x16x32_bf16 v[8:11], v[228:231], v[220:223], v[8:11]
	v_mfma_f32_16x16x32_bf16 v[0:3], v[236:239], v[220:223], v[0:3]
	v_mfma_f32_16x16x32_bf16 v[56:59], v[232:235], v[200:203], v[56:59]
	v_mfma_f32_16x16x32_bf16 v[48:51], v[240:243], v[200:203], v[48:51]
	v_mfma_f32_16x16x32_bf16 v[40:43], v[232:235], v[208:211], v[40:43]
	v_mfma_f32_16x16x32_bf16 v[32:35], v[240:243], v[208:211], v[32:35]
	v_mfma_f32_16x16x32_bf16 v[24:27], v[232:235], v[216:219], v[24:27]
	v_mfma_f32_16x16x32_bf16 v[16:19], v[240:243], v[216:219], v[16:19]
	v_mfma_f32_16x16x32_bf16 v[8:11], v[232:235], v[224:227], v[8:11]
	v_mfma_f32_16x16x32_bf16 v[0:3], v[240:243], v[224:227], v[0:3]
	s_barrier
	s_cbranch_scc0 .LBB0_213
	v_mul_f32_e32 v145, 0xbfb8aa3b, v124
	v_exp_f32_e32 v145, v145
	v_lshl_or_b32 v146, s38, 7, v142
	v_lshl_add_u32 v144, s39, 8, v140
	v_ashrrev_i32_e32 v147, 31, v146
	v_add_f32_e32 v145, 1.0, v145
	v_rcp_f32_e32 v145, v145
	v_mov_b64_e32 v[138:139], s[4:5]
	s_movk_i32 s7, 0x2c00
	v_mad_i64_i32 v[160:161], s[16:17], v144, s7, v[138:139]
	v_mul_f32_e32 v124, v124, v145
	v_mul_f32_e32 v120, v120, v124
	v_mul_f32_e32 v124, 0xbfb8aa3b, v125
	v_exp_f32_e32 v124, v124
	s_and_b64 vcc, exec, s[0:1]
	s_mov_b32 s38, s6
	s_mov_b32 s39, s10
	v_add_f32_e32 v124, 1.0, v124
	v_rcp_f32_e32 v124, v124
	s_mov_b64 s[20:21], s[14:15]
	v_mul_f32_e32 v124, v125, v124
	v_mul_f32_e32 v121, v121, v124
	v_mul_f32_e32 v124, 0xbfb8aa3b, v126
	v_exp_f32_e32 v124, v124
	s_nop 0
	v_add_f32_e32 v124, 1.0, v124
	v_rcp_f32_e32 v124, v124
	s_nop 0
	v_mul_f32_e32 v124, v126, v124
	v_mul_f32_e32 v122, v122, v124
	v_mul_f32_e32 v124, 0xbfb8aa3b, v127
	v_exp_f32_e32 v124, v124
	s_nop 0
	v_add_f32_e32 v124, 1.0, v124
	v_rcp_f32_e32 v124, v124
	s_nop 0
	v_mul_f32_e32 v124, v127, v124
	v_mul_f32_e32 v123, v123, v124
	v_mul_f32_e32 v124, 0xbfb8aa3b, v116
	v_exp_f32_e32 v124, v124
	s_nop 0
	v_add_f32_e32 v124, 1.0, v124
	v_rcp_f32_e32 v124, v124
	s_nop 0
	v_mul_f32_e32 v116, v116, v124
	v_mul_f32_e32 v116, v112, v116
	v_mul_f32_e32 v112, 0xbfb8aa3b, v117
	v_exp_f32_e32 v112, v112
	s_nop 0
	v_add_f32_e32 v112, 1.0, v112
	v_rcp_f32_e32 v112, v112
	s_nop 0
	v_mul_f32_e32 v112, v117, v112
	v_mul_f32_e32 v117, v113, v112
	v_mul_f32_e32 v112, 0xbfb8aa3b, v118
	v_exp_f32_e32 v112, v112
	v_cvt_pk_bf16_f32 v116, v116, v117
	s_nop 0
	v_add_f32_e32 v112, 1.0, v112
	v_rcp_f32_e32 v112, v112
	s_nop 0
	v_mul_f32_e32 v112, v118, v112
	v_mul_f32_e32 v124, v114, v112
	v_mul_f32_e32 v112, 0xbfb8aa3b, v119
	v_exp_f32_e32 v112, v112
	v_cvt_pk_bf16_f32 v114, v120, v121
	s_nop 0
	v_add_f32_e32 v112, 1.0, v112
	v_rcp_f32_e32 v112, v112
	s_nop 0
	v_mul_f32_e32 v112, v119, v112
	v_mul_f32_e32 v125, v115, v112
	v_lshlrev_b64 v[112:113], 1, v[146:147]
	v_lshl_add_u64 v[118:119], v[160:161], 0, v[112:113]
	v_cvt_pk_bf16_f32 v115, v122, v123
	v_cvt_pk_bf16_f32 v117, v124, v125
	global_store_dwordx4 v[118:119], v[114:117], off
	s_nop 1
	v_mul_f32_e32 v116, 0xbfb8aa3b, v108
	v_exp_f32_e32 v116, v116
	v_or_b32_e32 v114, 16, v144
	v_mad_i64_i32 v[114:115], s[16:17], v114, s7, v[138:139]
	v_add_f32_e32 v116, 1.0, v116
	v_rcp_f32_e32 v116, v116
	s_nop 0
	v_mul_f32_e32 v108, v108, v116
	v_mul_f32_e32 v104, v104, v108
	v_mul_f32_e32 v108, 0xbfb8aa3b, v109
	v_exp_f32_e32 v108, v108
	s_nop 0
	v_add_f32_e32 v108, 1.0, v108
	v_rcp_f32_e32 v108, v108
	s_nop 0
	v_mul_f32_e32 v108, v109, v108
	v_mul_f32_e32 v105, v105, v108
	v_mul_f32_e32 v108, 0xbfb8aa3b, v110
	v_exp_f32_e32 v108, v108
	s_nop 0
	v_add_f32_e32 v108, 1.0, v108
	v_rcp_f32_e32 v108, v108
	s_nop 0
	v_mul_f32_e32 v108, v110, v108
	v_mul_f32_e32 v106, v106, v108
	v_mul_f32_e32 v108, 0xbfb8aa3b, v111
	v_exp_f32_e32 v108, v108
	s_nop 0
	v_add_f32_e32 v108, 1.0, v108
	v_rcp_f32_e32 v108, v108
	s_nop 0
	v_mul_f32_e32 v108, v111, v108
	v_mul_f32_e32 v107, v107, v108
	v_mul_f32_e32 v108, 0xbfb8aa3b, v100
	v_exp_f32_e32 v108, v108
	s_nop 0
	v_add_f32_e32 v108, 1.0, v108
	v_rcp_f32_e32 v108, v108
	s_nop 0
	v_mul_f32_e32 v100, v100, v108
	v_mul_f32_e32 v108, v96, v100
	v_mul_f32_e32 v96, 0xbfb8aa3b, v101
	v_exp_f32_e32 v96, v96
	s_nop 0
	v_add_f32_e32 v96, 1.0, v96
	v_rcp_f32_e32 v96, v96
	s_nop 0
	v_mul_f32_e32 v96, v101, v96
	v_mul_f32_e32 v109, v97, v96
	v_mul_f32_e32 v96, 0xbfb8aa3b, v102
	v_exp_f32_e32 v96, v96
	v_lshl_add_u64 v[100:101], v[114:115], 0, v[112:113]
	v_cvt_pk_bf16_f32 v97, v106, v107
	v_add_f32_e32 v96, 1.0, v96
	v_rcp_f32_e32 v96, v96
	s_nop 0
	v_mul_f32_e32 v96, v102, v96
	v_mul_f32_e32 v102, v98, v96
	v_mul_f32_e32 v96, 0xbfb8aa3b, v103
	v_exp_f32_e32 v96, v96
	v_cvt_pk_bf16_f32 v98, v108, v109
	s_nop 0
	v_add_f32_e32 v96, 1.0, v96
	v_rcp_f32_e32 v96, v96
	s_nop 0
	v_mul_f32_e32 v96, v103, v96
	v_mul_f32_e32 v99, v99, v96
	v_cvt_pk_bf16_f32 v96, v104, v105
	v_cvt_pk_bf16_f32 v99, v102, v99
	global_store_dwordx4 v[100:101], v[96:99], off
	s_nop 1
; __device__ __forceinline__ unsigned cvt_pk_bf16(float lo, float hi) { unsigned r; asm("v_cvt_pk_bf16_f32 %0, %1, %2" : "=v"(r) : "v"(lo), "v"(hi)); return r; }
;     __device__ __forceinline__ void operator()(const f32x4 (&acc)[2][2][4][2], const Unit& u, int wr, int wc, int fr, int fq) const {
;     ...
;         for (int ai = 0; ai < 2; ++ai)
; #pragma unroll
;             for (int m = 0; m < 4; ++m) { bf16_t* rowp = O + (size_t)(row0 + ai * HALF + m * 16) * ldc + col0;
;                 float h[8];
; #pragma unroll
;                 for (int n = 0; n < 2; ++n)
; #pragma unroll
;                     for (int j = 0; j < 4; ++j) { const float g = acc[ai][0][m][n][j], up = acc[ai][1][m][n][j];
;                         const float e = __builtin_amdgcn_exp2f(-1.4426950408889634f * g);
;                         h[n * 4 + j] = g * __builtin_amdgcn_rcpf(1.0f + e) * up; }
;                 u32x4 w; w.x = cvt_pk_bf16(h[0], h[1]); w.y = cvt_pk_bf16(h[2], h[3]); w.z = cvt_pk_bf16(h[4], h[5]); w.w = cvt_pk_bf16(h[6], h[7]);
;                 *(u32x4*)rowp = w; }
	v_mul_f32_e32 v98, 0xbfb8aa3b, v92
	v_exp_f32_e32 v98, v98
	v_or_b32_e32 v96, 32, v144
	v_mad_i64_i32 v[96:97], s[16:17], v96, s7, v[138:139]
	v_add_f32_e32 v98, 1.0, v98
	v_rcp_f32_e32 v98, v98
	s_nop 0
	v_mul_f32_e32 v92, v92, v98
	v_mul_f32_e32 v88, v88, v92
	v_mul_f32_e32 v92, 0xbfb8aa3b, v93
	v_exp_f32_e32 v92, v92
	s_nop 0
	v_add_f32_e32 v92, 1.0, v92
	v_rcp_f32_e32 v92, v92
	s_nop 0
	v_mul_f32_e32 v92, v93, v92
	v_mul_f32_e32 v89, v89, v92
	v_mul_f32_e32 v92, 0xbfb8aa3b, v94
	v_exp_f32_e32 v92, v92
	s_nop 0
	v_add_f32_e32 v92, 1.0, v92
	v_rcp_f32_e32 v92, v92
	s_nop 0
	v_mul_f32_e32 v92, v94, v92
	v_mul_f32_e32 v90, v90, v92
	v_mul_f32_e32 v92, 0xbfb8aa3b, v95
	v_exp_f32_e32 v92, v92
	s_nop 0
	v_add_f32_e32 v92, 1.0, v92
	v_rcp_f32_e32 v92, v92
	s_nop 0
	v_mul_f32_e32 v92, v95, v92
	v_mul_f32_e32 v91, v91, v92
	v_mul_f32_e32 v92, 0xbfb8aa3b, v84
	v_exp_f32_e32 v92, v92
	s_nop 0
	v_add_f32_e32 v92, 1.0, v92
	v_rcp_f32_e32 v92, v92
	s_nop 0
	v_mul_f32_e32 v84, v84, v92
	v_mul_f32_e32 v92, v80, v84
	v_mul_f32_e32 v80, 0xbfb8aa3b, v85
	v_exp_f32_e32 v80, v80
	s_nop 0
	v_add_f32_e32 v80, 1.0, v80
	v_rcp_f32_e32 v80, v80
	s_nop 0
	v_mul_f32_e32 v80, v85, v80
	v_mul_f32_e32 v93, v81, v80
	v_mul_f32_e32 v80, 0xbfb8aa3b, v86
	v_exp_f32_e32 v80, v80
	v_lshl_add_u64 v[84:85], v[96:97], 0, v[112:113]
	v_cvt_pk_bf16_f32 v81, v90, v91
	v_add_f32_e32 v80, 1.0, v80
	v_rcp_f32_e32 v80, v80
	s_nop 0
	v_mul_f32_e32 v80, v86, v80
	v_mul_f32_e32 v86, v82, v80
	v_mul_f32_e32 v80, 0xbfb8aa3b, v87
	v_exp_f32_e32 v80, v80
	v_cvt_pk_bf16_f32 v82, v92, v93
	s_nop 0
	v_add_f32_e32 v80, 1.0, v80
	v_rcp_f32_e32 v80, v80
	s_nop 0
	v_mul_f32_e32 v80, v87, v80
	v_mul_f32_e32 v83, v83, v80
	v_cvt_pk_bf16_f32 v80, v88, v89
	v_cvt_pk_bf16_f32 v83, v86, v83
	global_store_dwordx4 v[84:85], v[80:83], off
	s_nop 1
	v_mul_f32_e32 v82, 0xbfb8aa3b, v76
	v_exp_f32_e32 v82, v82
	v_or_b32_e32 v80, 48, v144
	v_mad_i64_i32 v[80:81], s[16:17], v80, s7, v[138:139]
	v_add_f32_e32 v82, 1.0, v82
	v_rcp_f32_e32 v82, v82
	s_nop 0
	v_mul_f32_e32 v76, v76, v82
	v_mul_f32_e32 v72, v72, v76
	v_mul_f32_e32 v76, 0xbfb8aa3b, v77
	v_exp_f32_e32 v76, v76
	s_nop 0
	v_add_f32_e32 v76, 1.0, v76
	v_rcp_f32_e32 v76, v76
	s_nop 0
	v_mul_f32_e32 v76, v77, v76
	v_mul_f32_e32 v73, v73, v76
	v_mul_f32_e32 v76, 0xbfb8aa3b, v78
	v_exp_f32_e32 v76, v76
	s_nop 0
	v_add_f32_e32 v76, 1.0, v76
	v_rcp_f32_e32 v76, v76
	s_nop 0
	v_mul_f32_e32 v76, v78, v76
	v_mul_f32_e32 v74, v74, v76
	v_mul_f32_e32 v76, 0xbfb8aa3b, v79
	v_exp_f32_e32 v76, v76
	s_nop 0
	v_add_f32_e32 v76, 1.0, v76
	v_rcp_f32_e32 v76, v76
	s_nop 0
	v_mul_f32_e32 v76, v79, v76
	v_mul_f32_e32 v75, v75, v76
	v_mul_f32_e32 v76, 0xbfb8aa3b, v68
	v_exp_f32_e32 v76, v76
	s_nop 0
	v_add_f32_e32 v76, 1.0, v76
	v_rcp_f32_e32 v76, v76
	s_nop 0
	v_mul_f32_e32 v68, v68, v76
	v_mul_f32_e32 v76, v64, v68
	v_mul_f32_e32 v64, 0xbfb8aa3b, v69
	v_exp_f32_e32 v64, v64
	s_nop 0
	v_add_f32_e32 v64, 1.0, v64
	v_rcp_f32_e32 v64, v64
	s_nop 0
	v_mul_f32_e32 v64, v69, v64
	v_mul_f32_e32 v77, v65, v64
	v_mul_f32_e32 v64, 0xbfb8aa3b, v70
	v_exp_f32_e32 v64, v64
	v_lshl_add_u64 v[68:69], v[80:81], 0, v[112:113]
	v_cvt_pk_bf16_f32 v65, v74, v75
	v_add_f32_e32 v64, 1.0, v64
	v_rcp_f32_e32 v64, v64
	s_nop 0
	v_mul_f32_e32 v64, v70, v64
	v_mul_f32_e32 v70, v66, v64
	v_mul_f32_e32 v64, 0xbfb8aa3b, v71
	v_exp_f32_e32 v64, v64
	v_cvt_pk_bf16_f32 v66, v76, v77
	s_nop 0
	v_add_f32_e32 v64, 1.0, v64
	v_rcp_f32_e32 v64, v64
	s_nop 0
	v_mul_f32_e32 v64, v71, v64
	v_mul_f32_e32 v67, v67, v64
	v_cvt_pk_bf16_f32 v64, v72, v73
	v_cvt_pk_bf16_f32 v67, v70, v67
	global_store_dwordx4 v[68:69], v[64:67], off
	s_nop 1
	v_mul_f32_e32 v66, 0xbfb8aa3b, v60
	v_exp_f32_e32 v66, v66
	v_add_u32_e32 v64, 0x80, v144
	v_mad_i64_i32 v[64:65], s[16:17], v64, s7, v[138:139]
	v_add_f32_e32 v66, 1.0, v66
	v_rcp_f32_e32 v66, v66
	s_nop 0
	v_mul_f32_e32 v60, v60, v66
	v_mul_f32_e32 v56, v56, v60
	v_mul_f32_e32 v60, 0xbfb8aa3b, v61
	v_exp_f32_e32 v60, v60
	s_nop 0
	v_add_f32_e32 v60, 1.0, v60
	v_rcp_f32_e32 v60, v60
	s_nop 0
	v_mul_f32_e32 v60, v61, v60
	v_mul_f32_e32 v57, v57, v60
	v_mul_f32_e32 v60, 0xbfb8aa3b, v62
	v_exp_f32_e32 v60, v60
	s_nop 0
	v_add_f32_e32 v60, 1.0, v60
	v_rcp_f32_e32 v60, v60
	s_nop 0
	v_mul_f32_e32 v60, v62, v60
	v_mul_f32_e32 v58, v58, v60
	v_mul_f32_e32 v60, 0xbfb8aa3b, v63
	v_exp_f32_e32 v60, v60
	s_nop 0
	v_add_f32_e32 v60, 1.0, v60
	v_rcp_f32_e32 v60, v60
	s_nop 0
	v_mul_f32_e32 v60, v63, v60
	v_mul_f32_e32 v59, v59, v60
	v_mul_f32_e32 v60, 0xbfb8aa3b, v52
	v_exp_f32_e32 v60, v60
	s_nop 0
	v_add_f32_e32 v60, 1.0, v60
	v_rcp_f32_e32 v60, v60
	s_nop 0
	v_mul_f32_e32 v52, v52, v60
	v_mul_f32_e32 v60, v48, v52
	v_mul_f32_e32 v48, 0xbfb8aa3b, v53
	v_exp_f32_e32 v48, v48
	s_nop 0
	v_add_f32_e32 v48, 1.0, v48
	v_rcp_f32_e32 v48, v48
	s_nop 0
	v_mul_f32_e32 v48, v53, v48
	v_mul_f32_e32 v61, v49, v48
	v_mul_f32_e32 v48, 0xbfb8aa3b, v54
	v_exp_f32_e32 v48, v48
	v_lshl_add_u64 v[52:53], v[64:65], 0, v[112:113]
	v_cvt_pk_bf16_f32 v49, v58, v59
	v_add_f32_e32 v48, 1.0, v48
	v_rcp_f32_e32 v48, v48
	s_nop 0
	v_mul_f32_e32 v48, v54, v48
	v_mul_f32_e32 v54, v50, v48
	v_mul_f32_e32 v48, 0xbfb8aa3b, v55
	v_exp_f32_e32 v48, v48
	v_cvt_pk_bf16_f32 v50, v60, v61
	s_nop 0
	v_add_f32_e32 v48, 1.0, v48
	v_rcp_f32_e32 v48, v48
	s_nop 0
	v_mul_f32_e32 v48, v55, v48
	v_mul_f32_e32 v51, v51, v48
	v_cvt_pk_bf16_f32 v48, v56, v57
	v_cvt_pk_bf16_f32 v51, v54, v51
	global_store_dwordx4 v[52:53], v[48:51], off
	s_nop 1
	v_mul_f32_e32 v50, 0xbfb8aa3b, v44
; __device__ __forceinline__ unsigned cvt_pk_bf16(float lo, float hi) { unsigned r; asm("v_cvt_pk_bf16_f32 %0, %1, %2" : "=v"(r) : "v"(lo), "v"(hi)); return r; }
; #define PG8_WAIT_V(n) asm volatile("s_waitcnt vmcnt(" #n ")" ::: "memory")
; #define PG8_BAR __builtin_amdgcn_s_barrier()
;     __device__ __forceinline__ void operator()(const f32x4 (&acc)[2][2][4][2], const Unit& u, int wr, int wc, int fr, int fq) const {
;     ...
;         for (int ai = 0; ai < 2; ++ai)
; #pragma unroll
;             for (int m = 0; m < 4; ++m) { bf16_t* rowp = O + (size_t)(row0 + ai * HALF + m * 16) * ldc + col0;
;                 float h[8];
; #pragma unroll
;                 for (int n = 0; n < 2; ++n)
; #pragma unroll
;                     for (int j = 0; j < 4; ++j) { const float g = acc[ai][0][m][n][j], up = acc[ai][1][m][n][j];
;                         const float e = __builtin_amdgcn_exp2f(-1.4426950408889634f * g);
;                         h[n * 4 + j] = g * __builtin_amdgcn_rcpf(1.0f + e) * up; }
;                 u32x4 w; w.x = cvt_pk_bf16(h[0], h[1]); w.y = cvt_pk_bf16(h[2], h[3]); w.z = cvt_pk_bf16(h[4], h[5]); w.w = cvt_pk_bf16(h[6], h[7]);
;                 *(u32x4*)rowp = w; }
; template <class Epi, class Sched>
; __device__ __forceinline__ void gemm_phase(LAS unsigned char* lds, const Gemm g, const Sched& S, const Epi& E) {
;     ...
;         E(acc, cur, wr, wc, fr, fq);
;         if (!has_next) break;
; #pragma unroll
;         for (int a = 0; a < 2; ++a)
; #pragma unroll
;             for (int b = 0; b < 2; ++b)
; #pragma unroll
;                 for (int m = 0; m < 4; ++m)
; #pragma unroll
;                     for (int n = 0; n < 2; ++n) acc[a][b][m][n] = (f32x4){0.f, 0.f, 0.f, 0.f};
;         cur = nxt; cA = nA; cB = nB; ++ui;
;     }
;     PG8_WAIT_V(0);
;     if (wr == 0) PG8_BAR;
;     PG8_BAR;
	v_exp_f32_e32 v50, v50
	v_add_u32_e32 v48, 0x90, v144
	v_mad_i64_i32 v[48:49], s[16:17], v48, s7, v[138:139]
	v_add_f32_e32 v50, 1.0, v50
	v_rcp_f32_e32 v50, v50
	s_nop 0
	v_mul_f32_e32 v44, v44, v50
	v_mul_f32_e32 v40, v40, v44
	v_mul_f32_e32 v44, 0xbfb8aa3b, v45
	v_exp_f32_e32 v44, v44
	s_nop 0
	v_add_f32_e32 v44, 1.0, v44
	v_rcp_f32_e32 v44, v44
	s_nop 0
	v_mul_f32_e32 v44, v45, v44
	v_mul_f32_e32 v41, v41, v44
	v_mul_f32_e32 v44, 0xbfb8aa3b, v46
	v_exp_f32_e32 v44, v44
	s_nop 0
	v_add_f32_e32 v44, 1.0, v44
	v_rcp_f32_e32 v44, v44
	s_nop 0
	v_mul_f32_e32 v44, v46, v44
	v_mul_f32_e32 v42, v42, v44
	v_mul_f32_e32 v44, 0xbfb8aa3b, v47
	v_exp_f32_e32 v44, v44
	s_nop 0
	v_add_f32_e32 v44, 1.0, v44
	v_rcp_f32_e32 v44, v44
	s_nop 0
	v_mul_f32_e32 v44, v47, v44
	v_mul_f32_e32 v43, v43, v44
	v_mul_f32_e32 v44, 0xbfb8aa3b, v36
	v_exp_f32_e32 v44, v44
	s_nop 0
	v_add_f32_e32 v44, 1.0, v44
	v_rcp_f32_e32 v44, v44
	s_nop 0
	v_mul_f32_e32 v36, v36, v44
	v_mul_f32_e32 v44, v32, v36
	v_mul_f32_e32 v32, 0xbfb8aa3b, v37
	v_exp_f32_e32 v32, v32
	s_nop 0
	v_add_f32_e32 v32, 1.0, v32
	v_rcp_f32_e32 v32, v32
	s_nop 0
	v_mul_f32_e32 v32, v37, v32
	v_mul_f32_e32 v45, v33, v32
	v_mul_f32_e32 v32, 0xbfb8aa3b, v38
	v_exp_f32_e32 v32, v32
	v_lshl_add_u64 v[36:37], v[48:49], 0, v[112:113]
	v_cvt_pk_bf16_f32 v33, v42, v43
	v_add_f32_e32 v32, 1.0, v32
	v_rcp_f32_e32 v32, v32
	s_nop 0
	v_mul_f32_e32 v32, v38, v32
	v_mul_f32_e32 v38, v34, v32
	v_mul_f32_e32 v32, 0xbfb8aa3b, v39
	v_exp_f32_e32 v32, v32
	v_cvt_pk_bf16_f32 v34, v44, v45
	s_nop 0
	v_add_f32_e32 v32, 1.0, v32
	v_rcp_f32_e32 v32, v32
	s_nop 0
	v_mul_f32_e32 v32, v39, v32
	v_mul_f32_e32 v35, v35, v32
	v_cvt_pk_bf16_f32 v32, v40, v41
	v_cvt_pk_bf16_f32 v35, v38, v35
	global_store_dwordx4 v[36:37], v[32:35], off
	s_nop 1
	v_mul_f32_e32 v34, 0xbfb8aa3b, v28
	v_exp_f32_e32 v34, v34
	v_add_u32_e32 v32, 0xa0, v144
	v_mad_i64_i32 v[32:33], s[16:17], v32, s7, v[138:139]
	v_add_f32_e32 v34, 1.0, v34
	v_rcp_f32_e32 v34, v34
	s_nop 0
	v_mul_f32_e32 v28, v28, v34
	v_mul_f32_e32 v24, v24, v28
	v_mul_f32_e32 v28, 0xbfb8aa3b, v29
	v_exp_f32_e32 v28, v28
	s_nop 0
	v_add_f32_e32 v28, 1.0, v28
	v_rcp_f32_e32 v28, v28
	s_nop 0
	v_mul_f32_e32 v28, v29, v28
	v_mul_f32_e32 v25, v25, v28
	v_mul_f32_e32 v28, 0xbfb8aa3b, v30
	v_exp_f32_e32 v28, v28
	s_nop 0
	v_add_f32_e32 v28, 1.0, v28
	v_rcp_f32_e32 v28, v28
	s_nop 0
	v_mul_f32_e32 v28, v30, v28
	v_mul_f32_e32 v26, v26, v28
	v_mul_f32_e32 v28, 0xbfb8aa3b, v31
	v_exp_f32_e32 v28, v28
	s_nop 0
	v_add_f32_e32 v28, 1.0, v28
	v_rcp_f32_e32 v28, v28
	s_nop 0
	v_mul_f32_e32 v28, v31, v28
	v_mul_f32_e32 v27, v27, v28
	v_mul_f32_e32 v28, 0xbfb8aa3b, v20
	v_exp_f32_e32 v28, v28
	s_nop 0
	v_add_f32_e32 v28, 1.0, v28
	v_rcp_f32_e32 v28, v28
	s_nop 0
	v_mul_f32_e32 v20, v20, v28
	v_mul_f32_e32 v28, v16, v20
	v_mul_f32_e32 v16, 0xbfb8aa3b, v21
	v_exp_f32_e32 v16, v16
	s_nop 0
	v_add_f32_e32 v16, 1.0, v16
	v_rcp_f32_e32 v16, v16
	s_nop 0
	v_mul_f32_e32 v16, v21, v16
	v_mul_f32_e32 v29, v17, v16
	v_mul_f32_e32 v16, 0xbfb8aa3b, v22
	v_exp_f32_e32 v16, v16
	v_lshl_add_u64 v[20:21], v[32:33], 0, v[112:113]
	v_cvt_pk_bf16_f32 v17, v26, v27
	v_add_f32_e32 v16, 1.0, v16
	v_rcp_f32_e32 v16, v16
	s_nop 0
	v_mul_f32_e32 v16, v22, v16
	v_mul_f32_e32 v22, v18, v16
	v_mul_f32_e32 v16, 0xbfb8aa3b, v23
	v_exp_f32_e32 v16, v16
	v_cvt_pk_bf16_f32 v18, v28, v29
	s_nop 0
	v_add_f32_e32 v16, 1.0, v16
	v_rcp_f32_e32 v16, v16
	s_nop 0
	v_mul_f32_e32 v16, v23, v16
	v_mul_f32_e32 v19, v19, v16
	v_cvt_pk_bf16_f32 v16, v24, v25
	v_cvt_pk_bf16_f32 v19, v22, v19
	global_store_dwordx4 v[20:21], v[16:19], off
	s_nop 1
	v_mul_f32_e32 v18, 0xbfb8aa3b, v12
	v_exp_f32_e32 v18, v18
	v_add_u32_e32 v16, 0xb0, v144
	v_mad_i64_i32 v[16:17], s[16:17], v16, s7, v[138:139]
	v_add_f32_e32 v18, 1.0, v18
	v_rcp_f32_e32 v18, v18
	s_mov_b64 s[16:17], s[12:13]
	v_mul_f32_e32 v12, v12, v18
	v_mul_f32_e32 v8, v8, v12
	v_mul_f32_e32 v12, 0xbfb8aa3b, v13
	v_exp_f32_e32 v12, v12
	s_nop 0
	v_add_f32_e32 v12, 1.0, v12
	v_rcp_f32_e32 v12, v12
	s_nop 0
	v_mul_f32_e32 v12, v13, v12
	v_mul_f32_e32 v9, v9, v12
	v_mul_f32_e32 v12, 0xbfb8aa3b, v14
	v_exp_f32_e32 v12, v12
	s_nop 0
	v_add_f32_e32 v12, 1.0, v12
	v_rcp_f32_e32 v12, v12
	s_nop 0
	v_mul_f32_e32 v12, v14, v12
	v_mul_f32_e32 v10, v10, v12
	v_mul_f32_e32 v12, 0xbfb8aa3b, v15
	v_exp_f32_e32 v12, v12
	s_nop 0
	v_add_f32_e32 v12, 1.0, v12
	v_rcp_f32_e32 v12, v12
	s_nop 0
	v_mul_f32_e32 v12, v15, v12
	v_mul_f32_e32 v11, v11, v12
	v_mul_f32_e32 v12, 0xbfb8aa3b, v4
	v_exp_f32_e32 v12, v12
	s_nop 0
	v_add_f32_e32 v12, 1.0, v12
	v_rcp_f32_e32 v12, v12
	s_nop 0
	v_mul_f32_e32 v4, v4, v12
	v_mul_f32_e32 v12, v0, v4
	v_mul_f32_e32 v0, 0xbfb8aa3b, v5
	v_exp_f32_e32 v0, v0
	s_nop 0
	v_add_f32_e32 v0, 1.0, v0
	v_rcp_f32_e32 v0, v0
	s_nop 0
	v_mul_f32_e32 v0, v5, v0
	v_mul_f32_e32 v13, v1, v0
	v_mul_f32_e32 v0, 0xbfb8aa3b, v6
	v_exp_f32_e32 v0, v0
	v_lshl_add_u64 v[4:5], v[16:17], 0, v[112:113]
	v_cvt_pk_bf16_f32 v1, v10, v11
	v_add_f32_e32 v0, 1.0, v0
	v_rcp_f32_e32 v0, v0
	s_nop 0
	v_mul_f32_e32 v0, v6, v0
	v_mul_f32_e32 v6, v2, v0
	v_mul_f32_e32 v0, 0xbfb8aa3b, v7
	v_exp_f32_e32 v0, v0
	v_cvt_pk_bf16_f32 v2, v12, v13
	s_nop 0
	v_add_f32_e32 v0, 1.0, v0
	v_rcp_f32_e32 v0, v0
	s_nop 0
	v_mul_f32_e32 v0, v7, v0
	v_mul_f32_e32 v3, v3, v0
	v_cvt_pk_bf16_f32 v0, v8, v9
	v_cvt_pk_bf16_f32 v3, v6, v3
	global_store_dwordx4 v[4:5], v[0:3], off
	s_cbranch_vccz .LBB0_210
	s_waitcnt vmcnt(0)
	s_cmpk_gt_u32 s24, 0xff
	s_cbranch_scc1 .LBB0_217
	s_barrier

; #define PG8_STAGE(bufoff, gbase, voff) do { _Pragma("unroll") for (int _i = 0; _i < 2; ++_i) \
;         __builtin_amdgcn_global_load_lds((const unsigned*)((const char*)(gbase) + (voff)[_i]), (LAS unsigned*)(lds + (bufoff) + ldsw + _i * 8192), 16, 0, 0); } while (0)
; #define PG8_LDA(dst, b, h) do { _Pragma("unroll") for (int m = 0; m < 4; ++m) _Pragma("unroll") for (int k = 0; k < 2; ++k) dst[m][k] = *(const LAS bf16x8*)(lds + PG8_SA(b, h) + aoff + m * 2048 + k * 1024); } while (0)
; #define PG8_LDB(dst, b, h) do { _Pragma("unroll") for (int n = 0; n < 2; ++n) _Pragma("unroll") for (int k = 0; k < 2; ++k) dst[n][k] = *(const LAS bf16x8*)(lds + PG8_SB(b, h) + boff + n * 2048 + k * 1024); } while (0)
; #define PG8_MMA(ai, bj, At, Bt) do { __builtin_amdgcn_s_setprio(1); _Pragma("unroll") for (int m = 0; m < 4; ++m) _Pragma("unroll") for (int n = 0; n < 2; ++n) _Pragma("unroll") for (int k = 0; k < 2; ++k) \
;         acc[ai][bj][m][n] = __builtin_amdgcn_mfma_f32_16x16x32_bf16(Bt[n][k], At[m][k], acc[ai][bj][m][n], 0, 0, 0); __builtin_amdgcn_s_setprio(0); } while (0)
; #define PG8_WAIT_V(n) asm volatile("s_waitcnt vmcnt(" #n ")" ::: "memory")
; #define PG8_WAIT_L(n) asm volatile("s_waitcnt lgkmcnt(" #n ")" ::: "memory")
; #define PG8_BAR __builtin_amdgcn_s_barrier()
; template <class Epi, class Sched>
; __device__ __forceinline__ void gemm_phase(LAS unsigned char* lds, const Gemm g, const Sched& S, const Epi& E) {
;     ...
;             const bool last = (t == nt - 2);
;             const char* a1 = cA + (size_t)(t + 1) * kstep;
;             const char* a2 = last ? nA : cA + (size_t)(t + 2) * kstep; const char* b2 = last ? nB : cB + (size_t)(t + 2) * kstep;
;             const char* a3 = a2 + kstep; const char* b3 = b2 + kstep;
;             PG8_LDB(B0, 0, 0); PG8_SCHED; PG8_LDA(At, 0, 0); PG8_STAGE(PG8_SA(1, 1), a1 + hstep, voffA);
;             PG8_WAIT_L(8); PG8_BAR; PG8_WAIT_L(0); PG8_MMA(0, 0, At, B0); PG8_BAR; PG8_SCHED;
;             PG8_LDB(B1, 0, 1); PG8_STAGE(PG8_SB(0, 0), b2, voffB);
;             PG8_BAR; PG8_WAIT_L(0); PG8_MMA(0, 1, At, B1); PG8_BAR;
;             PG8_LDA(At, 0, 1); PG8_STAGE(PG8_SA(0, 0), a2, voffA);
;             PG8_BAR; PG8_WAIT_L(0); PG8_MMA(1, 0, At, B0); PG8_BAR; PG8_SCHED;
;             PG8_STAGE(PG8_SB(0, 1), b2 + hstep, voffB);
;             PG8_WAIT_V(6); PG8_BAR; PG8_MMA(1, 1, At, B1); PG8_BAR;
.LBB0_267:
	s_add_i32 s47, s22, 2
	s_add_u32 s20, s16, 0x100
	s_addc_u32 s21, s17, 0
	s_add_i32 s48, 0, 0x10000
	ds_read_b128 v[128:131], v161
	ds_read_b128 v[132:135], v161 offset:1024
	ds_read_b128 v[136:139], v161 offset:2048
	ds_read_b128 v[140:143], v161 offset:3072
	s_cmp_eq_u32 s11, s22
	s_cselect_b32 s22, s4, s13
	s_cselect_b32 s25, s7, s21
	s_cselect_b32 s24, s6, s20
	s_cselect_b32 s23, s5, s15
	s_add_i32 m0, s33, 0xc000
	ds_read_b128 v[144:147], v203
	ds_read_b128 v[166:169], v203 offset:1024
	ds_read_b128 v[170:173], v203 offset:2048
	ds_read_b128 v[174:177], v203 offset:3072
	ds_read_b128 v[204:207], v203 offset:4096
	ds_read_b128 v[208:211], v203 offset:5120
	ds_read_b128 v[212:215], v203 offset:6144
	ds_read_b128 v[216:219], v203 offset:7168
	global_load_lds_dwordx4 v162, s[16:17]
	s_add_i32 m0, s33, 0xe000
	s_nop 0
	global_load_lds_dwordx4 v164, s[16:17]
	s_waitcnt lgkmcnt(8)
	s_barrier
	s_waitcnt lgkmcnt(0)
	v_mfma_f32_16x16x32_bf16 v[124:127], v[128:131], v[144:147], v[124:127]
	v_mfma_f32_16x16x32_bf16 v[120:123], v[136:139], v[144:147], v[120:123]
	v_mfma_f32_16x16x32_bf16 v[116:119], v[128:131], v[170:173], v[116:119]
	v_mfma_f32_16x16x32_bf16 v[112:115], v[136:139], v[170:173], v[112:115]
	v_mfma_f32_16x16x32_bf16 v[100:103], v[128:131], v[204:207], v[100:103]
	v_mfma_f32_16x16x32_bf16 v[96:99], v[136:139], v[204:207], v[96:99]
	v_mfma_f32_16x16x32_bf16 v[84:87], v[128:131], v[212:215], v[84:87]
	v_mfma_f32_16x16x32_bf16 v[80:83], v[136:139], v[212:215], v[80:83]
	v_mfma_f32_16x16x32_bf16 v[124:127], v[132:135], v[166:169], v[124:127]
	v_mfma_f32_16x16x32_bf16 v[120:123], v[140:143], v[166:169], v[120:123]
	v_mfma_f32_16x16x32_bf16 v[116:119], v[132:135], v[174:177], v[116:119]
	v_mfma_f32_16x16x32_bf16 v[112:115], v[140:143], v[174:177], v[112:115]
	v_mfma_f32_16x16x32_bf16 v[100:103], v[132:135], v[208:211], v[100:103]
	v_mfma_f32_16x16x32_bf16 v[96:99], v[140:143], v[208:211], v[96:99]
	v_mfma_f32_16x16x32_bf16 v[84:87], v[132:135], v[216:219], v[84:87]
	v_mfma_f32_16x16x32_bf16 v[80:83], v[140:143], v[216:219], v[80:83]
	s_barrier
	s_add_i32 s49, 0, 0x14000
	s_add_i32 s16, s48, s31
	ds_read_b128 v[220:223], v161 offset:16384
	ds_read_b128 v[224:227], v161 offset:17408
	ds_read_b128 v[228:231], v161 offset:18432
	ds_read_b128 v[232:235], v161 offset:19456
	s_add_u32 s84, s22, 0x80
	s_addc_u32 s85, s23, 0
	s_mov_b32 m0, s16
	s_nop 0
	global_load_lds_dwordx4 v148, s[22:23]
	s_add_i32 m0, s16, 0x2000
	s_nop 0
	global_load_lds_dwordx4 v160, s[22:23]
	s_barrier
	s_waitcnt lgkmcnt(0)
	v_mfma_f32_16x16x32_bf16 v[108:111], v[220:223], v[144:147], v[108:111]
	v_mfma_f32_16x16x32_bf16 v[104:107], v[228:231], v[144:147], v[104:107]
	v_mfma_f32_16x16x32_bf16 v[92:95], v[220:223], v[170:173], v[92:95]
	v_mfma_f32_16x16x32_bf16 v[88:91], v[228:231], v[170:173], v[88:91]
	v_mfma_f32_16x16x32_bf16 v[76:79], v[220:223], v[204:207], v[76:79]
	v_mfma_f32_16x16x32_bf16 v[72:75], v[228:231], v[204:207], v[72:75]
	v_mfma_f32_16x16x32_bf16 v[68:71], v[220:223], v[212:215], v[68:71]
	v_mfma_f32_16x16x32_bf16 v[64:67], v[228:231], v[212:215], v[64:67]
	v_mfma_f32_16x16x32_bf16 v[108:111], v[224:227], v[166:169], v[108:111]
	v_mfma_f32_16x16x32_bf16 v[104:107], v[232:235], v[166:169], v[104:107]
	v_mfma_f32_16x16x32_bf16 v[92:95], v[224:227], v[174:177], v[92:95]
	v_mfma_f32_16x16x32_bf16 v[88:91], v[232:235], v[174:177], v[88:91]
	v_mfma_f32_16x16x32_bf16 v[76:79], v[224:227], v[208:211], v[76:79]
	v_mfma_f32_16x16x32_bf16 v[72:75], v[232:235], v[208:211], v[72:75]
	v_mfma_f32_16x16x32_bf16 v[68:71], v[224:227], v[216:219], v[68:71]
	v_mfma_f32_16x16x32_bf16 v[64:67], v[232:235], v[216:219], v[64:67]
	s_barrier
	s_mov_b32 m0, s33
	s_add_u32 s86, s24, 0x80
	s_addc_u32 s87, s25, 0
	ds_read_b128 v[144:147], v203 offset:16384
	ds_read_b128 v[166:169], v203 offset:17408
	ds_read_b128 v[170:173], v203 offset:18432
	ds_read_b128 v[174:177], v203 offset:19456
	ds_read_b128 v[204:207], v203 offset:20480
	ds_read_b128 v[208:211], v203 offset:21504
	ds_read_b128 v[212:215], v203 offset:22528
	ds_read_b128 v[216:219], v203 offset:23552
	global_load_lds_dwordx4 v148, s[24:25]
	s_mov_b32 m0, s34
	s_nop 0
	global_load_lds_dwordx4 v160, s[24:25]
	s_barrier
	s_waitcnt lgkmcnt(0)
	v_mfma_f32_16x16x32_bf16 v[60:63], v[128:131], v[144:147], v[60:63]
	v_mfma_f32_16x16x32_bf16 v[56:59], v[136:139], v[144:147], v[56:59]
	v_mfma_f32_16x16x32_bf16 v[52:55], v[128:131], v[170:173], v[52:55]
	v_mfma_f32_16x16x32_bf16 v[48:51], v[136:139], v[170:173], v[48:51]
	v_mfma_f32_16x16x32_bf16 v[36:39], v[128:131], v[204:207], v[36:39]
	v_mfma_f32_16x16x32_bf16 v[32:35], v[136:139], v[204:207], v[32:35]
	v_mfma_f32_16x16x32_bf16 v[20:23], v[128:131], v[212:215], v[20:23]
	v_mfma_f32_16x16x32_bf16 v[16:19], v[136:139], v[212:215], v[16:19]
	v_mfma_f32_16x16x32_bf16 v[60:63], v[132:135], v[166:169], v[60:63]
	v_mfma_f32_16x16x32_bf16 v[56:59], v[140:143], v[166:169], v[56:59]
	v_mfma_f32_16x16x32_bf16 v[52:55], v[132:135], v[174:177], v[52:55]
	v_mfma_f32_16x16x32_bf16 v[48:51], v[140:143], v[174:177], v[48:51]
	v_mfma_f32_16x16x32_bf16 v[36:39], v[132:135], v[208:211], v[36:39]
	v_mfma_f32_16x16x32_bf16 v[32:35], v[140:143], v[208:211], v[32:35]
	v_mfma_f32_16x16x32_bf16 v[20:23], v[132:135], v[216:219], v[20:23]
	v_mfma_f32_16x16x32_bf16 v[16:19], v[140:143], v[216:219], v[16:19]
	s_barrier
	s_add_u32 s16, s22, 0x80000
	s_addc_u32 s17, s23, 0
	s_add_i32 s48, s49, s31
	s_mov_b32 m0, s48
	s_nop 0
	global_load_lds_dwordx4 v148, s[16:17]
	s_add_i32 m0, s48, 0x2000
	s_nop 0
	global_load_lds_dwordx4 v160, s[16:17]
	s_waitcnt vmcnt(6)
	s_barrier
; #define PG8_STAGE(bufoff, gbase, voff) do { _Pragma("unroll") for (int _i = 0; _i < 2; ++_i) \
;         __builtin_amdgcn_global_load_lds((const unsigned*)((const char*)(gbase) + (voff)[_i]), (LAS unsigned*)(lds + (bufoff) + ldsw + _i * 8192), 16, 0, 0); } while (0)
; #define PG8_LDA(dst, b, h) do { _Pragma("unroll") for (int m = 0; m < 4; ++m) _Pragma("unroll") for (int k = 0; k < 2; ++k) dst[m][k] = *(const LAS bf16x8*)(lds + PG8_SA(b, h) + aoff + m * 2048 + k * 1024); } while (0)
; #define PG8_LDB(dst, b, h) do { _Pragma("unroll") for (int n = 0; n < 2; ++n) _Pragma("unroll") for (int k = 0; k < 2; ++k) dst[n][k] = *(const LAS bf16x8*)(lds + PG8_SB(b, h) + boff + n * 2048 + k * 1024); } while (0)
; #define PG8_MMA(ai, bj, At, Bt) do { __builtin_amdgcn_s_setprio(1); _Pragma("unroll") for (int m = 0; m < 4; ++m) _Pragma("unroll") for (int n = 0; n < 2; ++n) _Pragma("unroll") for (int k = 0; k < 2; ++k) \
;         acc[ai][bj][m][n] = __builtin_amdgcn_mfma_f32_16x16x32_bf16(Bt[n][k], At[m][k], acc[ai][bj][m][n], 0, 0, 0); __builtin_amdgcn_s_setprio(0); } while (0)
; #define PG8_WAIT_V(n) asm volatile("s_waitcnt vmcnt(" #n ")" ::: "memory")
; #define PG8_WAIT_L(n) asm volatile("s_waitcnt lgkmcnt(" #n ")" ::: "memory")
; #define PG8_BAR __builtin_amdgcn_s_barrier()
; #define PG8_SCHED __builtin_amdgcn_sched_barrier(0)
; template <class Epi, class Sched>
; __device__ __forceinline__ void gemm_phase(LAS unsigned char* lds, const Gemm g, const Sched& S, const Epi& E) {
;     ...
;             PG8_WAIT_V(6); PG8_BAR; PG8_MMA(1, 1, At, B1); PG8_BAR;
;             PG8_LDB(B0, 1, 0); PG8_SCHED; PG8_LDA(At, 1, 0); PG8_STAGE(PG8_SA(0, 1), a2 + hstep, voffA);
;             PG8_WAIT_L(8); PG8_BAR; PG8_WAIT_L(0); PG8_MMA(0, 0, At, B0); PG8_BAR; PG8_SCHED;
;             PG8_LDB(B1, 1, 1); PG8_STAGE(PG8_SB(1, 0), b3, voffB);
;             PG8_BAR; PG8_WAIT_L(0); PG8_MMA(0, 1, At, B1); PG8_BAR;
;             PG8_LDA(At, 1, 1); PG8_STAGE(PG8_SA(1, 0), a3, voffA);
;             PG8_BAR; PG8_WAIT_L(0); PG8_MMA(1, 0, At, B0); PG8_BAR; PG8_SCHED;
	v_mfma_f32_16x16x32_bf16 v[44:47], v[220:223], v[144:147], v[44:47]
	v_mfma_f32_16x16x32_bf16 v[40:43], v[228:231], v[144:147], v[40:43]
	v_mfma_f32_16x16x32_bf16 v[28:31], v[220:223], v[170:173], v[28:31]
	v_mfma_f32_16x16x32_bf16 v[24:27], v[228:231], v[170:173], v[24:27]
	v_mfma_f32_16x16x32_bf16 v[12:15], v[220:223], v[204:207], v[12:15]
	v_mfma_f32_16x16x32_bf16 v[8:11], v[228:231], v[204:207], v[8:11]
	v_mfma_f32_16x16x32_bf16 v[4:7], v[220:223], v[212:215], v[4:7]
	v_mfma_f32_16x16x32_bf16 v[0:3], v[228:231], v[212:215], v[0:3]
	v_mfma_f32_16x16x32_bf16 v[44:47], v[224:227], v[166:169], v[44:47]
	v_mfma_f32_16x16x32_bf16 v[40:43], v[232:235], v[166:169], v[40:43]
	v_mfma_f32_16x16x32_bf16 v[28:31], v[224:227], v[174:177], v[28:31]
	v_mfma_f32_16x16x32_bf16 v[24:27], v[232:235], v[174:177], v[24:27]
	v_mfma_f32_16x16x32_bf16 v[12:15], v[224:227], v[208:211], v[12:15]
	v_mfma_f32_16x16x32_bf16 v[8:11], v[232:235], v[208:211], v[8:11]
	v_mfma_f32_16x16x32_bf16 v[4:7], v[224:227], v[216:219], v[4:7]
	v_mfma_f32_16x16x32_bf16 v[0:3], v[232:235], v[216:219], v[0:3]
	s_barrier
	s_add_i32 s48, 0, 0x18000
	ds_read_b128 v[128:131], v161 offset:32768
	ds_read_b128 v[132:135], v161 offset:33792
	ds_read_b128 v[136:139], v161 offset:34816
	ds_read_b128 v[140:143], v161 offset:35840
	s_add_u32 s16, s24, 0x80000
	s_addc_u32 s17, s25, 0
	s_mov_b32 m0, s35
	ds_read_b128 v[144:147], v203 offset:32768
	ds_read_b128 v[166:169], v203 offset:33792
	ds_read_b128 v[170:173], v203 offset:34816
	ds_read_b128 v[174:177], v203 offset:35840
	ds_read_b128 v[204:207], v203 offset:36864
	ds_read_b128 v[208:211], v203 offset:37888
	ds_read_b128 v[212:215], v203 offset:38912
	ds_read_b128 v[216:219], v203 offset:39936
	global_load_lds_dwordx4 v148, s[16:17]
	s_mov_b32 m0, s36
	s_nop 0
	global_load_lds_dwordx4 v160, s[16:17]
	s_waitcnt lgkmcnt(8)
	s_barrier
	s_waitcnt lgkmcnt(0)
	v_mfma_f32_16x16x32_bf16 v[124:127], v[128:131], v[144:147], v[124:127]
	v_mfma_f32_16x16x32_bf16 v[120:123], v[136:139], v[144:147], v[120:123]
	v_mfma_f32_16x16x32_bf16 v[116:119], v[128:131], v[170:173], v[116:119]
	v_mfma_f32_16x16x32_bf16 v[112:115], v[136:139], v[170:173], v[112:115]
	v_mfma_f32_16x16x32_bf16 v[100:103], v[128:131], v[204:207], v[100:103]
	v_mfma_f32_16x16x32_bf16 v[96:99], v[136:139], v[204:207], v[96:99]
	v_mfma_f32_16x16x32_bf16 v[84:87], v[128:131], v[212:215], v[84:87]
	v_mfma_f32_16x16x32_bf16 v[80:83], v[136:139], v[212:215], v[80:83]
	v_mfma_f32_16x16x32_bf16 v[124:127], v[132:135], v[166:169], v[124:127]
	v_mfma_f32_16x16x32_bf16 v[120:123], v[140:143], v[166:169], v[120:123]
	v_mfma_f32_16x16x32_bf16 v[116:119], v[132:135], v[174:177], v[116:119]
	v_mfma_f32_16x16x32_bf16 v[112:115], v[140:143], v[174:177], v[112:115]
	v_mfma_f32_16x16x32_bf16 v[100:103], v[132:135], v[208:211], v[100:103]
	v_mfma_f32_16x16x32_bf16 v[96:99], v[140:143], v[208:211], v[96:99]
	v_mfma_f32_16x16x32_bf16 v[84:87], v[132:135], v[216:219], v[84:87]
	v_mfma_f32_16x16x32_bf16 v[80:83], v[140:143], v[216:219], v[80:83]
	s_barrier
	s_add_i32 s24, 0, 0x1c000
	s_add_i32 s16, s48, s31
	s_mov_b32 m0, s16
	ds_read_b128 v[220:223], v161 offset:49152
	ds_read_b128 v[224:227], v161 offset:50176
	ds_read_b128 v[228:231], v161 offset:51200
	ds_read_b128 v[232:235], v161 offset:52224
	global_load_lds_dwordx4 v148, s[84:85]
	s_add_i32 m0, s16, 0x2000
	s_nop 0
	global_load_lds_dwordx4 v160, s[84:85]
	s_barrier
	s_waitcnt lgkmcnt(0)
	v_mfma_f32_16x16x32_bf16 v[108:111], v[220:223], v[144:147], v[108:111]
	v_mfma_f32_16x16x32_bf16 v[104:107], v[228:231], v[144:147], v[104:107]
	v_mfma_f32_16x16x32_bf16 v[92:95], v[220:223], v[170:173], v[92:95]
	v_mfma_f32_16x16x32_bf16 v[88:91], v[228:231], v[170:173], v[88:91]
	v_mfma_f32_16x16x32_bf16 v[76:79], v[220:223], v[204:207], v[76:79]
	v_mfma_f32_16x16x32_bf16 v[72:75], v[228:231], v[204:207], v[72:75]
	v_mfma_f32_16x16x32_bf16 v[68:71], v[220:223], v[212:215], v[68:71]
	v_mfma_f32_16x16x32_bf16 v[64:67], v[228:231], v[212:215], v[64:67]
	v_mfma_f32_16x16x32_bf16 v[108:111], v[224:227], v[166:169], v[108:111]
	v_mfma_f32_16x16x32_bf16 v[104:107], v[232:235], v[166:169], v[104:107]
	v_mfma_f32_16x16x32_bf16 v[92:95], v[224:227], v[174:177], v[92:95]
	v_mfma_f32_16x16x32_bf16 v[88:91], v[232:235], v[174:177], v[88:91]
	v_mfma_f32_16x16x32_bf16 v[76:79], v[224:227], v[208:211], v[76:79]
	v_mfma_f32_16x16x32_bf16 v[72:75], v[232:235], v[208:211], v[72:75]
	v_mfma_f32_16x16x32_bf16 v[68:71], v[224:227], v[216:219], v[68:71]
	v_mfma_f32_16x16x32_bf16 v[64:67], v[232:235], v[216:219], v[64:67]
	s_barrier
	s_mov_b32 m0, s39
	ds_read_b128 v[144:147], v203 offset:49152
	ds_read_b128 v[166:169], v203 offset:50176
	ds_read_b128 v[170:173], v203 offset:51200
	ds_read_b128 v[174:177], v203 offset:52224
	ds_read_b128 v[204:207], v203 offset:53248
	ds_read_b128 v[208:211], v203 offset:54272
	ds_read_b128 v[212:215], v203 offset:55296
	ds_read_b128 v[216:219], v203 offset:56320
	global_load_lds_dwordx4 v148, s[86:87]
	s_mov_b32 m0, s40
	s_nop 0
	global_load_lds_dwordx4 v160, s[86:87]
	s_barrier
	s_waitcnt lgkmcnt(0)
	v_mfma_f32_16x16x32_bf16 v[60:63], v[128:131], v[144:147], v[60:63]
	v_mfma_f32_16x16x32_bf16 v[56:59], v[136:139], v[144:147], v[56:59]
	v_mfma_f32_16x16x32_bf16 v[52:55], v[128:131], v[170:173], v[52:55]
	v_mfma_f32_16x16x32_bf16 v[48:51], v[136:139], v[170:173], v[48:51]
	v_mfma_f32_16x16x32_bf16 v[36:39], v[128:131], v[204:207], v[36:39]
	v_mfma_f32_16x16x32_bf16 v[32:35], v[136:139], v[204:207], v[32:35]
	v_mfma_f32_16x16x32_bf16 v[20:23], v[128:131], v[212:215], v[20:23]
	v_mfma_f32_16x16x32_bf16 v[16:19], v[136:139], v[212:215], v[16:19]
	v_mfma_f32_16x16x32_bf16 v[60:63], v[132:135], v[166:169], v[60:63]
	v_mfma_f32_16x16x32_bf16 v[56:59], v[140:143], v[166:169], v[56:59]
	v_mfma_f32_16x16x32_bf16 v[52:55], v[132:135], v[174:177], v[52:55]
	v_mfma_f32_16x16x32_bf16 v[48:51], v[140:143], v[174:177], v[48:51]
	v_mfma_f32_16x16x32_bf16 v[36:39], v[132:135], v[208:211], v[36:39]
	v_mfma_f32_16x16x32_bf16 v[32:35], v[140:143], v[208:211], v[32:35]
	v_mfma_f32_16x16x32_bf16 v[20:23], v[132:135], v[216:219], v[20:23]
	v_mfma_f32_16x16x32_bf16 v[16:19], v[140:143], v[216:219], v[16:19]
	s_barrier
; #define PG8_STAGE(bufoff, gbase, voff) do { _Pragma("unroll") for (int _i = 0; _i < 2; ++_i) \
;         __builtin_amdgcn_global_load_lds((const unsigned*)((const char*)(gbase) + (voff)[_i]), (LAS unsigned*)(lds + (bufoff) + ldsw + _i * 8192), 16, 0, 0); } while (0)
; #define PG8_WAIT_V(n) asm volatile("s_waitcnt vmcnt(" #n ")" ::: "memory")
; #define PG8_BAR __builtin_amdgcn_s_barrier()
;     __device__ __forceinline__ void operator()(const f32x4 (&acc)[2][2][4][2], const Unit& u, int wr, int wc, int fr, int fq) const {
;         const int row0 = u.pm * BM + wr * 64 + fr, col0 = u.pn * BM + wc * 32 + 4 * fq;
;         if (u.slice >= 0) {
;             float* pb = P + (size_t)u.slice * 512 * DM;
; #pragma unroll
;             for (int ai = 0; ai < 2; ++ai)
; #pragma unroll
;                 for (int m = 0; m < 4; ++m) { const size_t off = (size_t)(row0 - MP + ai * HALF + m * 16) * DM + col0;
; #pragma unroll
;                     for (int bj = 0; bj < 2; ++bj)
; #pragma unroll
;                         for (int n = 0; n < 2; ++n) *(f32x4*)(pb + off + bj * HALF + n * 16) = acc[ai][bj][m][n]; }
;             return;
;         }
;         const float* base = (u.pm < 32) ? base_lo : base_hi;
; #pragma unroll
;         for (int ai = 0; ai < 2; ++ai) {
;             f32x4 bs[4][2][2];
; #pragma unroll
;             for (int m = 0; m < 4; ++m) { const size_t off = (size_t)(row0 + ai * HALF + m * 16) * DM + col0;
; #pragma unroll
;                 for (int bj = 0; bj < 2; ++bj)
; #pragma unroll
;                     for (int n = 0; n < 2; ++n) bs[m][bj][n] = *(const f32x4*)(base + off + bj * HALF + n * 16); }
; #pragma unroll
;             for (int m = 0; m < 4; ++m) { const size_t off = (size_t)(row0 + ai * HALF + m * 16) * DM + col0;
; #pragma unroll
;                 for (int bj = 0; bj < 2; ++bj)
; #pragma unroll
;                     for (int n = 0; n < 2; ++n) *(f32x4*)(out + off + bj * HALF + n * 16) = bs[m][bj][n] + scale * acc[ai][bj][m][n]; }
; template <class Epi, class Sched>
; __device__ __forceinline__ void gemm_phase(LAS unsigned char* lds, const Gemm g, const Sched& S, const Epi& E) {
;     ...
;             PG8_STAGE(PG8_SB(1, 1), b3 + hstep, voffB);
;             PG8_WAIT_V(6); PG8_BAR; PG8_MMA(1, 1, At, B1); PG8_BAR;
	s_add_u32 s16, s22, 0x80080
	s_addc_u32 s17, s23, 0
	s_add_i32 s22, s24, s31
	s_mov_b32 m0, s22
	s_nop 0
	global_load_lds_dwordx4 v148, s[16:17]
	s_add_i32 m0, s22, 0x2000
	s_nop 0
	global_load_lds_dwordx4 v160, s[16:17]
	s_waitcnt vmcnt(6)
	s_barrier
	v_mfma_f32_16x16x32_bf16 v[44:47], v[220:223], v[144:147], v[44:47]
	v_mfma_f32_16x16x32_bf16 v[40:43], v[228:231], v[144:147], v[40:43]
	v_mfma_f32_16x16x32_bf16 v[28:31], v[220:223], v[170:173], v[28:31]
	v_mfma_f32_16x16x32_bf16 v[24:27], v[228:231], v[170:173], v[24:27]
	v_mfma_f32_16x16x32_bf16 v[12:15], v[220:223], v[204:207], v[12:15]
	v_mfma_f32_16x16x32_bf16 v[8:11], v[228:231], v[204:207], v[8:11]
	v_mfma_f32_16x16x32_bf16 v[4:7], v[220:223], v[212:215], v[4:7]
	v_mfma_f32_16x16x32_bf16 v[0:3], v[228:231], v[212:215], v[0:3]
	v_mfma_f32_16x16x32_bf16 v[44:47], v[224:227], v[166:169], v[44:47]
	v_mfma_f32_16x16x32_bf16 v[40:43], v[232:235], v[166:169], v[40:43]
	v_mfma_f32_16x16x32_bf16 v[28:31], v[224:227], v[174:177], v[28:31]
	v_mfma_f32_16x16x32_bf16 v[24:27], v[232:235], v[174:177], v[24:27]
	v_mfma_f32_16x16x32_bf16 v[12:15], v[224:227], v[208:211], v[12:15]
	v_mfma_f32_16x16x32_bf16 v[8:11], v[232:235], v[208:211], v[8:11]
	v_mfma_f32_16x16x32_bf16 v[4:7], v[224:227], v[216:219], v[4:7]
	v_mfma_f32_16x16x32_bf16 v[0:3], v[232:235], v[216:219], v[0:3]
	s_add_u32 s13, s13, 0x100
	s_addc_u32 s15, s15, 0
	s_cmp_ge_i32 s47, s45
	s_mov_b64 s[16:17], s[20:21]
	s_mov_b32 s22, s47
	s_barrier
	s_cbranch_scc0 .LBB0_267
	v_lshl_add_u32 v166, s46, 8, v200
	v_lshl_or_b32 v168, s44, 8, v202
	s_mov_b64 s[16:17], -1
	s_cmp_lt_i32 s82, 0
	v_ashrrev_i32_e32 v169, 31, v168
	v_ashrrev_i32_e32 v167, 31, v166
	s_cbranch_scc0 .LBB0_270
	v_lshlrev_b64 v[170:171], 2, v[168:169]
	v_lshl_add_u64 v[172:173], s[60:61], 0, v[170:171]
	v_lshlrev_b64 v[174:175], 13, v[166:167]
	v_lshl_add_u64 v[128:129], v[172:173], 0, v[174:175]
	global_load_dwordx4 v[204:207], v[128:129], off
	global_load_dwordx4 v[208:211], v[128:129], off offset:64
	global_load_dwordx4 v[212:215], v[128:129], off offset:512
	global_load_dwordx4 v[216:219], v[128:129], off offset:576
	v_or_b32_e32 v128, 16, v166
	v_ashrrev_i32_e32 v129, 31, v128
	v_lshlrev_b64 v[188:189], 13, v[128:129]
	v_lshl_add_u64 v[128:129], v[172:173], 0, v[188:189]
	global_load_dwordx4 v[220:223], v[128:129], off
	global_load_dwordx4 v[224:227], v[128:129], off offset:64
	global_load_dwordx4 v[228:231], v[128:129], off offset:512
	global_load_dwordx4 v[232:235], v[128:129], off offset:576
	v_or_b32_e32 v128, 32, v166
	v_ashrrev_i32_e32 v129, 31, v128
	v_lshlrev_b64 v[190:191], 13, v[128:129]
	v_lshl_add_u64 v[128:129], v[172:173], 0, v[190:191]
	global_load_dwordx4 v[236:239], v[128:129], off
	global_load_dwordx4 v[240:243], v[128:129], off offset:64
	global_load_dwordx4 v[144:147], v[128:129], off offset:512
	global_load_dwordx4 v[140:143], v[128:129], off offset:576
	v_or_b32_e32 v128, 48, v166
	v_ashrrev_i32_e32 v129, 31, v128
	v_lshlrev_b64 v[176:177], 13, v[128:129]
	v_lshl_add_u64 v[128:129], v[172:173], 0, v[176:177]
	global_load_dwordx4 v[244:247], v[128:129], off
	global_load_dwordx4 v[136:139], v[128:129], off offset:64
	global_load_dwordx4 v[132:135], v[128:129], off offset:512
	s_nop 0
	global_load_dwordx4 v[128:131], v[128:129], off offset:576
	v_lshl_add_u64 v[248:249], s[60:61], 0, v[174:175]
	v_lshl_add_u64 v[248:249], v[248:249], 0, v[170:171]
	v_lshl_add_u64 v[188:189], s[60:61], 0, v[188:189]
	v_lshl_add_u64 v[188:189], v[188:189], 0, v[170:171]
	s_mov_b64 s[16:17], 0x100000
	s_waitcnt vmcnt(0)
	v_pk_add_f32 v[206:207], v[206:207], v[126:127]
	v_pk_add_f32 v[204:205], v[204:205], v[124:125]
	global_store_dwordx4 v[248:249], v[204:207], off
	v_pk_add_f32 v[146:147], v[146:147], v[78:79]
	s_nop 0
	v_pk_add_f32 v[206:207], v[210:211], v[122:123]
	v_pk_add_f32 v[204:205], v[208:209], v[120:121]
	global_store_dwordx4 v[248:249], v[204:207], off offset:64
	v_pk_add_f32 v[144:145], v[144:145], v[76:77]
	v_pk_add_f32 v[142:143], v[142:143], v[74:75]
	v_pk_add_f32 v[206:207], v[214:215], v[110:111]
	v_pk_add_f32 v[204:205], v[212:213], v[108:109]
	global_store_dwordx4 v[248:249], v[204:207], off offset:512
	v_pk_add_f32 v[140:141], v[140:141], v[72:73]
	v_pk_add_f32 v[138:139], v[138:139], v[82:83]
	v_pk_add_f32 v[206:207], v[218:219], v[106:107]
	v_pk_add_f32 v[204:205], v[216:217], v[104:105]
	global_store_dwordx4 v[248:249], v[204:207], off offset:576
	v_pk_add_f32 v[136:137], v[136:137], v[80:81]
	v_pk_add_f32 v[134:135], v[134:135], v[70:71]
	v_pk_add_f32 v[206:207], v[222:223], v[118:119]
	v_pk_add_f32 v[204:205], v[220:221], v[116:117]
	global_store_dwordx4 v[188:189], v[204:207], off
	v_pk_add_f32 v[132:133], v[132:133], v[68:69]
	v_pk_add_f32 v[130:131], v[130:131], v[66:67]
	v_pk_add_f32 v[206:207], v[226:227], v[114:115]
	v_pk_add_f32 v[204:205], v[224:225], v[112:113]
	global_store_dwordx4 v[188:189], v[204:207], off offset:64
	v_pk_add_f32 v[128:129], v[128:129], v[64:65]
	s_nop 0
	v_pk_add_f32 v[206:207], v[230:231], v[94:95]
	v_pk_add_f32 v[204:205], v[228:229], v[92:93]
	global_store_dwordx4 v[188:189], v[204:207], off offset:512
	s_nop 1
	v_pk_add_f32 v[206:207], v[234:235], v[90:91]
	v_pk_add_f32 v[204:205], v[232:233], v[88:89]
	global_store_dwordx4 v[188:189], v[204:207], off offset:576
;     __device__ __forceinline__ void operator()(const f32x4 (&acc)[2][2][4][2], const Unit& u, int wr, int wc, int fr, int fq) const {
;     ...
;         for (int ai = 0; ai < 2; ++ai) {
;             f32x4 bs[4][2][2];
; #pragma unroll
;             for (int m = 0; m < 4; ++m) { const size_t off = (size_t)(row0 + ai * HALF + m * 16) * DM + col0;
; #pragma unroll
;                 for (int bj = 0; bj < 2; ++bj)
; #pragma unroll
;                     for (int n = 0; n < 2; ++n) bs[m][bj][n] = *(const f32x4*)(base + off + bj * HALF + n * 16); }
; #pragma unroll
;             for (int m = 0; m < 4; ++m) { const size_t off = (size_t)(row0 + ai * HALF + m * 16) * DM + col0;
; #pragma unroll
;                 for (int bj = 0; bj < 2; ++bj)
; #pragma unroll
;                     for (int n = 0; n < 2; ++n) *(f32x4*)(out + off + bj * HALF + n * 16) = bs[m][bj][n] + scale * acc[ai][bj][m][n]; }
	v_lshl_add_u64 v[188:189], s[60:61], 0, v[190:191]
	v_lshl_add_u64 v[188:189], v[188:189], 0, v[170:171]
	v_pk_add_f32 v[206:207], v[238:239], v[102:103]
	v_pk_add_f32 v[204:205], v[236:237], v[100:101]
	global_store_dwordx4 v[188:189], v[144:147], off offset:512
	global_store_dwordx4 v[188:189], v[204:207], off
	global_store_dwordx4 v[188:189], v[140:143], off offset:576
	v_lshl_add_u64 v[144:145], s[60:61], 0, v[176:177]
	v_pk_add_f32 v[206:207], v[242:243], v[98:99]
	v_pk_add_f32 v[204:205], v[240:241], v[96:97]
	v_pk_add_f32 v[142:143], v[246:247], v[86:87]
	v_pk_add_f32 v[140:141], v[244:245], v[84:85]
	v_lshl_add_u64 v[144:145], v[144:145], 0, v[170:171]
	global_store_dwordx4 v[188:189], v[204:207], off offset:64
	global_store_dwordx4 v[144:145], v[140:143], off
	global_store_dwordx4 v[144:145], v[136:139], off offset:64
	global_store_dwordx4 v[144:145], v[132:135], off offset:512
	global_store_dwordx4 v[144:145], v[128:131], off offset:576
	v_lshl_add_u64 v[146:147], v[174:175], 0, s[16:17]
	s_mov_b64 s[16:17], 0x120000
	v_lshl_add_u64 v[128:129], v[172:173], 0, v[146:147]
	global_load_dwordx4 v[142:145], v[128:129], off
	global_load_dwordx4 v[204:207], v[128:129], off offset:64
	global_load_dwordx4 v[208:211], v[128:129], off offset:512
	global_load_dwordx4 v[212:215], v[128:129], off offset:576
	v_lshl_add_u64 v[176:177], v[174:175], 0, s[16:17]
	v_lshl_add_u64 v[128:129], v[172:173], 0, v[176:177]
	global_load_dwordx4 v[216:219], v[128:129], off
	global_load_dwordx4 v[220:223], v[128:129], off offset:64
	global_load_dwordx4 v[224:227], v[128:129], off offset:512
	global_load_dwordx4 v[228:231], v[128:129], off offset:576
	s_mov_b64 s[16:17], 0x140000
	v_lshl_add_u64 v[188:189], v[174:175], 0, s[16:17]
	s_mov_b64 s[16:17], 0x160000
	v_lshl_add_u64 v[128:129], v[172:173], 0, v[188:189]
	v_lshl_add_u64 v[140:141], v[174:175], 0, s[16:17]
	global_load_dwordx4 v[232:235], v[128:129], off
	global_load_dwordx4 v[236:239], v[128:129], off offset:64
	global_load_dwordx4 v[240:243], v[128:129], off offset:512
	global_load_dwordx4 v[244:247], v[128:129], off offset:576
	v_lshl_add_u64 v[128:129], v[172:173], 0, v[140:141]
	global_load_dwordx4 v[172:175], v[128:129], off
	global_load_dwordx4 v[136:139], v[128:129], off offset:64
	global_load_dwordx4 v[132:135], v[128:129], off offset:512
	s_nop 0
	global_load_dwordx4 v[128:131], v[128:129], off offset:576
	v_lshl_add_u64 v[146:147], s[60:61], 0, v[146:147]
	v_lshl_add_u64 v[146:147], v[146:147], 0, v[170:171]
	v_lshl_add_u64 v[140:141], s[60:61], 0, v[140:141]
	v_lshl_add_u64 v[140:141], v[140:141], 0, v[170:171]
	s_mov_b64 s[16:17], 0
	s_waitcnt vmcnt(0)
	v_pk_add_f32 v[144:145], v[62:63], v[144:145]
	v_pk_add_f32 v[142:143], v[60:61], v[142:143]
	global_store_dwordx4 v[146:147], v[142:145], off
	v_pk_add_f32 v[138:139], v[18:19], v[138:139]
	s_nop 0
	v_pk_add_f32 v[144:145], v[58:59], v[206:207]
	v_pk_add_f32 v[142:143], v[56:57], v[204:205]
	global_store_dwordx4 v[146:147], v[142:145], off offset:64
	v_pk_add_f32 v[136:137], v[16:17], v[136:137]
	v_pk_add_f32 v[134:135], v[6:7], v[134:135]
	v_pk_add_f32 v[144:145], v[46:47], v[210:211]
	v_pk_add_f32 v[142:143], v[44:45], v[208:209]
	global_store_dwordx4 v[146:147], v[142:145], off offset:512
	v_pk_add_f32 v[132:133], v[4:5], v[132:133]
	v_pk_add_f32 v[130:131], v[2:3], v[130:131]
	v_pk_add_f32 v[144:145], v[42:43], v[214:215]
	v_pk_add_f32 v[142:143], v[40:41], v[212:213]
	global_store_dwordx4 v[146:147], v[142:145], off offset:576
	v_lshl_add_u64 v[146:147], s[60:61], 0, v[176:177]
	v_lshl_add_u64 v[146:147], v[146:147], 0, v[170:171]
	v_pk_add_f32 v[144:145], v[54:55], v[218:219]
	v_pk_add_f32 v[142:143], v[52:53], v[216:217]
	global_store_dwordx4 v[146:147], v[142:145], off
	v_pk_add_f32 v[128:129], v[0:1], v[128:129]
	global_store_dwordx4 v[140:141], v[136:139], off offset:64
	v_pk_add_f32 v[144:145], v[50:51], v[222:223]
	v_pk_add_f32 v[142:143], v[48:49], v[220:221]
	global_store_dwordx4 v[146:147], v[142:145], off offset:64
	global_store_dwordx4 v[140:141], v[132:135], off offset:512
	global_store_dwordx4 v[140:141], v[128:131], off offset:576
	v_pk_add_f32 v[144:145], v[30:31], v[226:227]
	v_pk_add_f32 v[142:143], v[28:29], v[224:225]
	global_store_dwordx4 v[146:147], v[142:145], off offset:512
	s_nop 1
	v_pk_add_f32 v[144:145], v[26:27], v[230:231]
	v_pk_add_f32 v[142:143], v[24:25], v[228:229]
	global_store_dwordx4 v[146:147], v[142:145], off offset:576
	v_lshl_add_u64 v[146:147], s[60:61], 0, v[188:189]
	v_lshl_add_u64 v[146:147], v[146:147], 0, v[170:171]
	v_pk_add_f32 v[144:145], v[38:39], v[234:235]
	v_pk_add_f32 v[142:143], v[36:37], v[232:233]
	global_store_dwordx4 v[146:147], v[142:145], off
	s_nop 1
	v_pk_add_f32 v[144:145], v[34:35], v[238:239]
	v_pk_add_f32 v[142:143], v[32:33], v[236:237]
	global_store_dwordx4 v[146:147], v[142:145], off offset:64
	s_nop 1
	v_pk_add_f32 v[144:145], v[14:15], v[242:243]
	v_pk_add_f32 v[142:143], v[12:13], v[240:241]
	global_store_dwordx4 v[146:147], v[142:145], off offset:512
	s_nop 1
	v_pk_add_f32 v[144:145], v[10:11], v[246:247]
	v_pk_add_f32 v[142:143], v[8:9], v[244:245]
	global_store_dwordx4 v[146:147], v[142:145], off offset:576
	s_nop 1
	v_pk_add_f32 v[144:145], v[22:23], v[174:175]
	v_pk_add_f32 v[142:143], v[20:21], v[172:173]
	global_store_dwordx4 v[140:141], v[142:145], off
